# variant of the static-priority version: the trailing group's raise is kept through the unit epilogues and dropped at the grid barriers
# baseline (speedup 1.0000x reference)
.LBB0_180:
	v_lshrrev_b32_e32 v1, 20, v0
	v_lshrrev_b32_e32 v0, 10, v0
	s_waitcnt lgkmcnt(0)
	s_barrier
	s_waitcnt vmcnt(0) lgkmcnt(0)
	v_or_b32_e32 v0, v0, v1
	s_movk_i32 s0, 0x3ff
	v_and_or_b32 v0, v0, s0, v195
	v_cmp_eq_u32_e32 vcc, 0, v0
	s_barrier
	s_and_saveexec_b64 s[0:1], vcc
	v_readlane_b32 s72, v252, 2
	v_readlane_b32 s73, v252, 3
	s_cbranch_execz .LBB0_190
	s_setprio 0
	buffer_wbl2 sc1
	s_waitcnt vmcnt(0)
	v_readlane_b32 s4, v252, 0
	v_readlane_b32 s5, v252, 1
	s_add_u32 s4, s4, 0x36b0
	s_addc_u32 s5, s5, 0
	v_mov_b32_e32 v2, 0
	v_mov_b32_e32 v3, 1
	s_nop 4
	global_atomic_add v2, v3, s[4:5]

.Lsprio_0:
.LBB0_214:
	s_add_u32 s28, s30, 0xfffc0080
	s_addc_u32 s36, s31, -1
	s_add_i32 s43, 0, 0x10000
	s_cmp_eq_u32 s26, 12
	s_cselect_b32 s53, s2, s36
	s_cselect_b32 s52, s3, s28
	v_add_u32_e32 v157, s43, v153
	s_cselect_b32 s37, s13, s25
	s_cselect_b32 s36, s16, s24
	s_add_i32 s28, 0, 0x14000
	ds_read_b128 v[130:133], v157
	ds_read_b128 v[148:151], v157 offset:1024
	ds_read_b128 v[158:161], v157 offset:2048
	ds_read_b128 v[162:165], v157 offset:3072
	v_add_u32_e32 v157, s28, v153
	ds_read_b128 v[166:169], v157
	ds_read_b128 v[170:173], v157 offset:1024
	ds_read_b128 v[174:177], v157 offset:2048
	ds_read_b128 v[178:181], v157 offset:3072
	v_lshl_add_u64 v[192:193], s[30:31], 0, v[144:145]
	s_add_i32 m0, s75, 0xc000
	ds_read_b128 v[184:187], v156
	ds_read_b128 v[188:191], v156 offset:1024
	ds_read_b128 v[196:199], v156 offset:2048
	ds_read_b128 v[210:213], v156 offset:3072
	ds_read_b128 v[214:217], v156 offset:4096
	ds_read_b128 v[218:221], v156 offset:5120
	ds_read_b128 v[222:225], v156 offset:6144
	ds_read_b128 v[226:229], v156 offset:7168
	global_load_lds_dwordx4 v[192:193], off
	v_lshl_add_u64 v[192:193], s[30:31], 0, v[146:147]
	s_add_i32 m0, s75, 0xe000
	s_nop 0
	global_load_lds_dwordx4 v[192:193], off
	s_waitcnt vmcnt(8)
	s_waitcnt lgkmcnt(0)
	s_barrier
	s_waitcnt lgkmcnt(0)
	v_mfma_f32_16x16x32_bf16 v[126:129], v[130:133], v[184:187], v[126:129]
	v_mfma_f32_16x16x32_bf16 v[122:125], v[158:161], v[184:187], v[122:125]
	v_mfma_f32_16x16x32_bf16 v[110:113], v[130:133], v[196:199], v[110:113]
	v_mfma_f32_16x16x32_bf16 v[106:109], v[158:161], v[196:199], v[106:109]
	v_mfma_f32_16x16x32_bf16 v[94:97], v[130:133], v[214:217], v[94:97]
	v_mfma_f32_16x16x32_bf16 v[90:93], v[158:161], v[214:217], v[90:93]
	v_mfma_f32_16x16x32_bf16 v[78:81], v[130:133], v[222:225], v[78:81]
	v_mfma_f32_16x16x32_bf16 v[74:77], v[158:161], v[222:225], v[74:77]
	v_mfma_f32_16x16x32_bf16 v[126:129], v[148:151], v[188:191], v[126:129]
	v_mfma_f32_16x16x32_bf16 v[122:125], v[162:165], v[188:191], v[122:125]
	v_mfma_f32_16x16x32_bf16 v[110:113], v[148:151], v[210:213], v[110:113]
	v_mfma_f32_16x16x32_bf16 v[106:109], v[162:165], v[210:213], v[106:109]
	v_mfma_f32_16x16x32_bf16 v[94:97], v[148:151], v[218:221], v[94:97]
	v_mfma_f32_16x16x32_bf16 v[90:93], v[162:165], v[218:221], v[90:93]
	v_mfma_f32_16x16x32_bf16 v[78:81], v[148:151], v[226:229], v[78:81]
	v_mfma_f32_16x16x32_bf16 v[74:77], v[162:165], v[226:229], v[74:77]
	v_mfma_f32_16x16x32_bf16 v[118:121], v[166:169], v[184:187], v[118:121]
	v_mfma_f32_16x16x32_bf16 v[114:117], v[174:177], v[184:187], v[114:117]
	v_mfma_f32_16x16x32_bf16 v[102:105], v[166:169], v[196:199], v[102:105]
	v_mfma_f32_16x16x32_bf16 v[98:101], v[174:177], v[196:199], v[98:101]
	v_mfma_f32_16x16x32_bf16 v[86:89], v[166:169], v[214:217], v[86:89]
	v_mfma_f32_16x16x32_bf16 v[82:85], v[174:177], v[214:217], v[82:85]
	v_mfma_f32_16x16x32_bf16 v[70:73], v[166:169], v[222:225], v[70:73]
	v_mfma_f32_16x16x32_bf16 v[66:69], v[174:177], v[222:225], v[66:69]
	v_mfma_f32_16x16x32_bf16 v[118:121], v[170:173], v[188:191], v[118:121]
	v_mfma_f32_16x16x32_bf16 v[114:117], v[178:181], v[188:191], v[114:117]
	v_mfma_f32_16x16x32_bf16 v[102:105], v[170:173], v[210:213], v[102:105]
	v_mfma_f32_16x16x32_bf16 v[98:101], v[178:181], v[210:213], v[98:101]
	v_mfma_f32_16x16x32_bf16 v[86:89], v[170:173], v[218:221], v[86:89]
	v_mfma_f32_16x16x32_bf16 v[82:85], v[178:181], v[218:221], v[82:85]
	v_mfma_f32_16x16x32_bf16 v[70:73], v[170:173], v[226:229], v[70:73]
	v_mfma_f32_16x16x32_bf16 v[66:69], v[178:181], v[226:229], v[66:69]
	s_barrier
	s_add_i32 s43, s43, s17
	v_lshl_add_u64 v[192:193], s[36:37], 0, v[0:1]
	s_mov_b32 m0, s43
	ds_read_b128 v[184:187], v156 offset:16384
	ds_read_b128 v[188:191], v156 offset:17408
	ds_read_b128 v[196:199], v156 offset:18432
	ds_read_b128 v[210:213], v156 offset:19456
	ds_read_b128 v[214:217], v156 offset:20480
	ds_read_b128 v[218:221], v156 offset:21504
	ds_read_b128 v[222:225], v156 offset:22528
	ds_read_b128 v[226:229], v156 offset:23552
	global_load_lds_dwordx4 v[192:193], off
	s_add_i32 m0, s43, 0x2000
	s_add_u32 s70, s36, 0x40000
	v_lshl_add_u64 v[202:203], s[36:37], 0, v[134:135]
	s_addc_u32 s71, s37, 0
	s_add_i32 s28, s28, s17
	global_load_lds_dwordx4 v[202:203], off
	v_lshl_add_u64 v[230:231], s[70:71], 0, v[0:1]
	s_mov_b32 m0, s28
	v_lshl_add_u64 v[232:233], s[52:53], 0, v[136:137]
	global_load_lds_dwordx4 v[230:231], off
	v_lshl_add_u64 v[230:231], s[70:71], 0, v[134:135]
	s_add_i32 m0, s28, 0x2000
	s_nop 0
	global_load_lds_dwordx4 v[230:231], off
	v_lshl_add_u64 v[230:231], s[52:53], 0, v[138:139]
	s_mov_b32 m0, s75
	s_nop 0
	global_load_lds_dwordx4 v[230:231], off
	s_mov_b32 m0, s58
	s_nop 0
	global_load_lds_dwordx4 v[232:233], off
	s_waitcnt vmcnt(8)
	s_waitcnt lgkmcnt(0)
	s_barrier
	s_waitcnt lgkmcnt(0)
	v_mfma_f32_16x16x32_bf16 v[62:65], v[130:133], v[184:187], v[62:65]
	v_mfma_f32_16x16x32_bf16 v[58:61], v[158:161], v[184:187], v[58:61]
	v_mfma_f32_16x16x32_bf16 v[46:49], v[130:133], v[196:199], v[46:49]
	v_mfma_f32_16x16x32_bf16 v[42:45], v[158:161], v[196:199], v[42:45]
	v_mfma_f32_16x16x32_bf16 v[30:33], v[130:133], v[214:217], v[30:33]
	v_mfma_f32_16x16x32_bf16 v[26:29], v[158:161], v[214:217], v[26:29]
	v_mfma_f32_16x16x32_bf16 v[14:17], v[130:133], v[222:225], v[14:17]
	v_mfma_f32_16x16x32_bf16 v[10:13], v[158:161], v[222:225], v[10:13]
	v_mfma_f32_16x16x32_bf16 v[62:65], v[148:151], v[188:191], v[62:65]
	v_mfma_f32_16x16x32_bf16 v[58:61], v[162:165], v[188:191], v[58:61]
	v_mfma_f32_16x16x32_bf16 v[46:49], v[148:151], v[210:213], v[46:49]
	v_mfma_f32_16x16x32_bf16 v[42:45], v[162:165], v[210:213], v[42:45]
	v_mfma_f32_16x16x32_bf16 v[30:33], v[148:151], v[218:221], v[30:33]
	v_mfma_f32_16x16x32_bf16 v[26:29], v[162:165], v[218:221], v[26:29]
	v_mfma_f32_16x16x32_bf16 v[14:17], v[148:151], v[226:229], v[14:17]
	v_mfma_f32_16x16x32_bf16 v[10:13], v[162:165], v[226:229], v[10:13]
	v_mfma_f32_16x16x32_bf16 v[54:57], v[166:169], v[184:187], v[54:57]
	v_mfma_f32_16x16x32_bf16 v[50:53], v[174:177], v[184:187], v[50:53]
	v_mfma_f32_16x16x32_bf16 v[38:41], v[166:169], v[196:199], v[38:41]
	v_mfma_f32_16x16x32_bf16 v[34:37], v[174:177], v[196:199], v[34:37]
	v_mfma_f32_16x16x32_bf16 v[22:25], v[166:169], v[214:217], v[22:25]
	v_mfma_f32_16x16x32_bf16 v[18:21], v[174:177], v[214:217], v[18:21]
	v_mfma_f32_16x16x32_bf16 v[6:9], v[166:169], v[222:225], v[6:9]
	v_mfma_f32_16x16x32_bf16 v[2:5], v[174:177], v[222:225], v[2:5]
	v_mfma_f32_16x16x32_bf16 v[54:57], v[170:173], v[188:191], v[54:57]
	v_mfma_f32_16x16x32_bf16 v[50:53], v[178:181], v[188:191], v[50:53]
	v_mfma_f32_16x16x32_bf16 v[38:41], v[170:173], v[210:213], v[38:41]
	v_mfma_f32_16x16x32_bf16 v[34:37], v[178:181], v[210:213], v[34:37]
	v_mfma_f32_16x16x32_bf16 v[22:25], v[170:173], v[218:221], v[22:25]
	v_mfma_f32_16x16x32_bf16 v[18:21], v[178:181], v[218:221], v[18:21]
	v_mfma_f32_16x16x32_bf16 v[6:9], v[170:173], v[226:229], v[6:9]
	v_mfma_f32_16x16x32_bf16 v[2:5], v[178:181], v[226:229], v[2:5]
	s_barrier
	s_add_i32 s28, 0, 0x18000
	v_add_u32_e32 v157, s28, v153
	s_add_i32 s43, 0, 0x1c000
	ds_read_b128 v[130:133], v157
	ds_read_b128 v[148:151], v157 offset:1024
	ds_read_b128 v[158:161], v157 offset:2048
	ds_read_b128 v[162:165], v157 offset:3072
	v_add_u32_e32 v157, s43, v153
	ds_read_b128 v[166:169], v157
	ds_read_b128 v[170:173], v157 offset:1024
	ds_read_b128 v[174:177], v157 offset:2048
	ds_read_b128 v[178:181], v157 offset:3072
	s_add_u32 s52, s52, 0x40000
	s_addc_u32 s53, s53, 0
	s_mov_b32 m0, s59
	v_lshl_add_u64 v[234:235], s[52:53], 0, v[138:139]
	ds_read_b128 v[184:187], v156 offset:32768
	ds_read_b128 v[188:191], v156 offset:33792
	ds_read_b128 v[196:199], v156 offset:34816
	ds_read_b128 v[210:213], v156 offset:35840
	ds_read_b128 v[214:217], v156 offset:36864
	ds_read_b128 v[218:221], v156 offset:37888
	ds_read_b128 v[222:225], v156 offset:38912
	ds_read_b128 v[226:229], v156 offset:39936
	global_load_lds_dwordx4 v[234:235], off
	v_lshl_add_u64 v[234:235], s[52:53], 0, v[136:137]
	s_mov_b32 m0, s60
	s_nop 0
	global_load_lds_dwordx4 v[234:235], off
	s_waitcnt vmcnt(8)
	s_waitcnt lgkmcnt(0)
	s_barrier
	s_waitcnt lgkmcnt(0)
	v_mfma_f32_16x16x32_bf16 v[126:129], v[130:133], v[184:187], v[126:129]
	v_mfma_f32_16x16x32_bf16 v[122:125], v[158:161], v[184:187], v[122:125]
	v_mfma_f32_16x16x32_bf16 v[110:113], v[130:133], v[196:199], v[110:113]
	v_mfma_f32_16x16x32_bf16 v[106:109], v[158:161], v[196:199], v[106:109]
	v_mfma_f32_16x16x32_bf16 v[94:97], v[130:133], v[214:217], v[94:97]
	v_mfma_f32_16x16x32_bf16 v[90:93], v[158:161], v[214:217], v[90:93]
	v_mfma_f32_16x16x32_bf16 v[78:81], v[130:133], v[222:225], v[78:81]
	v_mfma_f32_16x16x32_bf16 v[74:77], v[158:161], v[222:225], v[74:77]
	v_mfma_f32_16x16x32_bf16 v[126:129], v[148:151], v[188:191], v[126:129]
	v_mfma_f32_16x16x32_bf16 v[122:125], v[162:165], v[188:191], v[122:125]
	v_mfma_f32_16x16x32_bf16 v[110:113], v[148:151], v[210:213], v[110:113]
	v_mfma_f32_16x16x32_bf16 v[106:109], v[162:165], v[210:213], v[106:109]
	v_mfma_f32_16x16x32_bf16 v[94:97], v[148:151], v[218:221], v[94:97]
	v_mfma_f32_16x16x32_bf16 v[90:93], v[162:165], v[218:221], v[90:93]
	v_mfma_f32_16x16x32_bf16 v[78:81], v[148:151], v[226:229], v[78:81]
	v_mfma_f32_16x16x32_bf16 v[74:77], v[162:165], v[226:229], v[74:77]
	v_mfma_f32_16x16x32_bf16 v[118:121], v[166:169], v[184:187], v[118:121]
	v_mfma_f32_16x16x32_bf16 v[114:117], v[174:177], v[184:187], v[114:117]
	v_mfma_f32_16x16x32_bf16 v[102:105], v[166:169], v[196:199], v[102:105]
	v_mfma_f32_16x16x32_bf16 v[98:101], v[174:177], v[196:199], v[98:101]
	v_mfma_f32_16x16x32_bf16 v[86:89], v[166:169], v[214:217], v[86:89]
	v_mfma_f32_16x16x32_bf16 v[82:85], v[174:177], v[214:217], v[82:85]
	v_mfma_f32_16x16x32_bf16 v[70:73], v[166:169], v[222:225], v[70:73]
	v_mfma_f32_16x16x32_bf16 v[66:69], v[174:177], v[222:225], v[66:69]
	v_mfma_f32_16x16x32_bf16 v[118:121], v[170:173], v[188:191], v[118:121]
	v_mfma_f32_16x16x32_bf16 v[114:117], v[178:181], v[188:191], v[114:117]
	v_mfma_f32_16x16x32_bf16 v[102:105], v[170:173], v[210:213], v[102:105]
	v_mfma_f32_16x16x32_bf16 v[98:101], v[178:181], v[210:213], v[98:101]
	v_mfma_f32_16x16x32_bf16 v[86:89], v[170:173], v[218:221], v[86:89]
	v_mfma_f32_16x16x32_bf16 v[82:85], v[178:181], v[218:221], v[82:85]
	v_mfma_f32_16x16x32_bf16 v[70:73], v[170:173], v[226:229], v[70:73]
	v_mfma_f32_16x16x32_bf16 v[66:69], v[178:181], v[226:229], v[66:69]
	s_barrier
	s_add_i32 s28, s28, s17
	v_lshl_add_u64 v[192:193], v[192:193], 0, s[22:23]
	s_mov_b32 m0, s28
	ds_read_b128 v[184:187], v156 offset:49152
	ds_read_b128 v[188:191], v156 offset:50176
	ds_read_b128 v[196:199], v156 offset:51200
	ds_read_b128 v[210:213], v156 offset:52224
	ds_read_b128 v[214:217], v156 offset:53248
	ds_read_b128 v[218:221], v156 offset:54272
	ds_read_b128 v[222:225], v156 offset:55296
	ds_read_b128 v[226:229], v156 offset:56320
	global_load_lds_dwordx4 v[192:193], off
	s_add_i32 m0, s28, 0x2000
	s_add_u32 s36, s36, 0x40080
	v_lshl_add_u64 v[192:193], v[202:203], 0, s[22:23]
	s_addc_u32 s37, s37, 0
	s_add_i32 s28, s43, s17
	global_load_lds_dwordx4 v[192:193], off
	v_lshl_add_u64 v[192:193], s[36:37], 0, v[0:1]
	s_mov_b32 m0, s28
	s_nop 0
	global_load_lds_dwordx4 v[192:193], off
	v_lshl_add_u64 v[192:193], s[36:37], 0, v[134:135]
	s_add_i32 m0, s28, 0x2000
	s_nop 0
	global_load_lds_dwordx4 v[192:193], off
	v_lshl_add_u64 v[192:193], v[230:231], 0, s[22:23]
	s_mov_b32 m0, s62
	s_nop 0
	global_load_lds_dwordx4 v[192:193], off
	v_lshl_add_u64 v[192:193], v[232:233], 0, s[22:23]
	s_mov_b32 m0, s63
	s_nop 0
	global_load_lds_dwordx4 v[192:193], off
	s_waitcnt vmcnt(8)
	s_waitcnt lgkmcnt(0)
	s_barrier
	s_waitcnt lgkmcnt(0)
	v_mfma_f32_16x16x32_bf16 v[62:65], v[130:133], v[184:187], v[62:65]
	v_mfma_f32_16x16x32_bf16 v[58:61], v[158:161], v[184:187], v[58:61]
	v_mfma_f32_16x16x32_bf16 v[46:49], v[130:133], v[196:199], v[46:49]
	v_mfma_f32_16x16x32_bf16 v[42:45], v[158:161], v[196:199], v[42:45]
	v_mfma_f32_16x16x32_bf16 v[30:33], v[130:133], v[214:217], v[30:33]
	v_mfma_f32_16x16x32_bf16 v[26:29], v[158:161], v[214:217], v[26:29]
	v_mfma_f32_16x16x32_bf16 v[14:17], v[130:133], v[222:225], v[14:17]
	v_mfma_f32_16x16x32_bf16 v[10:13], v[158:161], v[222:225], v[10:13]
	v_mfma_f32_16x16x32_bf16 v[62:65], v[148:151], v[188:191], v[62:65]
	v_mfma_f32_16x16x32_bf16 v[58:61], v[162:165], v[188:191], v[58:61]
	v_mfma_f32_16x16x32_bf16 v[46:49], v[148:151], v[210:213], v[46:49]
	v_mfma_f32_16x16x32_bf16 v[42:45], v[162:165], v[210:213], v[42:45]
	v_mfma_f32_16x16x32_bf16 v[30:33], v[148:151], v[218:221], v[30:33]
	v_mfma_f32_16x16x32_bf16 v[26:29], v[162:165], v[218:221], v[26:29]
	v_mfma_f32_16x16x32_bf16 v[14:17], v[148:151], v[226:229], v[14:17]
	v_mfma_f32_16x16x32_bf16 v[10:13], v[162:165], v[226:229], v[10:13]
	v_mfma_f32_16x16x32_bf16 v[54:57], v[166:169], v[184:187], v[54:57]
	v_mfma_f32_16x16x32_bf16 v[50:53], v[174:177], v[184:187], v[50:53]
	v_mfma_f32_16x16x32_bf16 v[38:41], v[166:169], v[196:199], v[38:41]
	v_mfma_f32_16x16x32_bf16 v[34:37], v[174:177], v[196:199], v[34:37]
	v_mfma_f32_16x16x32_bf16 v[22:25], v[166:169], v[214:217], v[22:25]
	v_mfma_f32_16x16x32_bf16 v[18:21], v[174:177], v[214:217], v[18:21]
	v_mfma_f32_16x16x32_bf16 v[6:9], v[166:169], v[222:225], v[6:9]
	v_mfma_f32_16x16x32_bf16 v[2:5], v[174:177], v[222:225], v[2:5]
	v_mfma_f32_16x16x32_bf16 v[54:57], v[170:173], v[188:191], v[54:57]
	v_mfma_f32_16x16x32_bf16 v[50:53], v[178:181], v[188:191], v[50:53]
	v_mfma_f32_16x16x32_bf16 v[38:41], v[170:173], v[210:213], v[38:41]
	v_mfma_f32_16x16x32_bf16 v[34:37], v[178:181], v[210:213], v[34:37]
	v_mfma_f32_16x16x32_bf16 v[22:25], v[170:173], v[218:221], v[22:25]
	v_mfma_f32_16x16x32_bf16 v[18:21], v[178:181], v[218:221], v[18:21]
	v_mfma_f32_16x16x32_bf16 v[6:9], v[170:173], v[226:229], v[6:9]
	v_mfma_f32_16x16x32_bf16 v[2:5], v[178:181], v[226:229], v[2:5]
	s_barrier
	s_add_i32 s26, s26, 2
	s_add_u32 s30, s30, 0x100
	s_addc_u32 s31, s31, 0
	s_add_u32 s24, s24, 0x100
	s_addc_u32 s25, s25, 0
	s_cmp_gt_u32 s26, 13
	s_cbranch_scc0 .LBB0_214
	s_and_b64 vcc, exec, s[34:35]
	s_cbranch_vccz .LBB0_227
	s_barrier
	v_lshl_add_u32 v148, s12, 8, v152
	s_cmp_lt_i32 s74, s64
	s_mov_b64 s[12:13], -1
	s_cbranch_scc0 .LBB0_228

.LBB0_267:
	s_andn2_saveexec_b64 s[2:3], s[10:11]
	s_cbranch_execz .LBB0_287
	s_mov_b64 s[10:11], exec
	s_setprio 0
	buffer_wbl2 sc1
	s_waitcnt lgkmcnt(0)
	s_waitcnt vmcnt(0)
	v_mbcnt_lo_u32_b32 v0, s10, 0
	v_mbcnt_hi_u32_b32 v0, s11, v0
	v_cmp_eq_u32_e32 vcc, 0, v0
	s_and_saveexec_b64 s[12:13], vcc
	s_cbranch_execz .LBB0_270
	s_bcnt1_i32_b64 s0, s[10:11]
	v_readlane_b32 s2, v253, 61
	v_mov_b32_e32 v3, s0
	v_readlane_b32 s3, v253, 62
	s_nop 4
	global_atomic_add v3, v1, v3, s[2:3] sc0

.LBB0_331:
	s_andn2_saveexec_b64 s[2:3], s[8:9]
	s_cbranch_execz .LBB0_351
	s_mov_b64 s[8:9], exec
	s_setprio 0
	buffer_wbl2 sc1
	s_waitcnt lgkmcnt(0)
	s_waitcnt vmcnt(0)
	v_mbcnt_lo_u32_b32 v0, s8, 0
	v_mbcnt_hi_u32_b32 v0, s9, v0
	v_cmp_eq_u32_e32 vcc, 0, v0
	s_and_saveexec_b64 s[10:11], vcc
	s_cbranch_execz .LBB0_334
	s_bcnt1_i32_b64 s0, s[8:9]
	v_readlane_b32 s2, v253, 61
	v_mov_b32_e32 v3, s0
	v_readlane_b32 s3, v253, 62
	s_nop 4
	global_atomic_add v3, v1, v3, s[2:3] sc0

.LBB0_662:
	s_andn2_saveexec_b64 s[2:3], s[6:7]
	s_cbranch_execz .LBB0_682
	s_mov_b64 s[6:7], exec
	s_setprio 0
	buffer_wbl2 sc1
	s_waitcnt lgkmcnt(0)
	s_waitcnt vmcnt(0)
	v_mbcnt_lo_u32_b32 v0, s6, 0
	v_mbcnt_hi_u32_b32 v0, s7, v0
	v_cmp_eq_u32_e32 vcc, 0, v0
	s_and_saveexec_b64 s[8:9], vcc
	s_cbranch_execz .LBB0_665
	s_bcnt1_i32_b64 s0, s[6:7]
	v_readlane_b32 s2, v253, 61
	v_mov_b32_e32 v3, s0
	v_readlane_b32 s3, v253, 62
	s_nop 4
	global_atomic_add v3, v1, v3, s[2:3] sc0

.Lsprio_1:
.LBB0_695:
	s_add_u32 s30, s12, 0xfffc0080
	s_addc_u32 s31, s13, -1
	s_add_i32 s45, 0, 0x10000
	s_cmp_eq_u32 s35, 12
	s_cselect_b32 s37, s3, s31
	s_cselect_b32 s36, s16, s30
	s_cselect_b32 s31, s24, s28
	s_cselect_b32 s30, s25, s26
	s_add_i32 s59, 0, 0x14000
	v_add_u32_e32 v156, s45, v145
	v_add_u32_e32 v172, s59, v145
	ds_read_b128 v[140:143], v156
	ds_read_b128 v[148:151], v156 offset:1024
	ds_read_b128 v[152:155], v156 offset:2048
	ds_read_b128 v[156:159], v156 offset:3072
	ds_read_b128 v[160:163], v172
	ds_read_b128 v[164:167], v172 offset:1024
	ds_read_b128 v[168:171], v172 offset:2048
	ds_read_b128 v[172:175], v172 offset:3072
	v_lshl_add_u64 v[180:181], s[12:13], 0, v[136:137]
	s_add_i32 m0, s51, 0xc000
	ds_read_b128 v[176:179], v147
	ds_read_b128 v[184:187], v147 offset:1024
	ds_read_b128 v[188:191], v147 offset:2048
	ds_read_b128 v[196:199], v147 offset:3072
	ds_read_b128 v[210:213], v147 offset:4096
	ds_read_b128 v[214:217], v147 offset:5120
	ds_read_b128 v[218:221], v147 offset:6144
	ds_read_b128 v[222:225], v147 offset:7168
	global_load_lds_dwordx4 v[180:181], off
	v_lshl_add_u64 v[180:181], s[12:13], 0, v[138:139]
	s_add_i32 m0, s51, 0xe000
	s_nop 0
	global_load_lds_dwordx4 v[180:181], off
	s_waitcnt vmcnt(8)
	s_waitcnt lgkmcnt(0)
	s_barrier
	s_waitcnt lgkmcnt(0)
	v_mfma_f32_16x16x32_bf16 v[126:129], v[140:143], v[176:179], v[126:129]
	v_mfma_f32_16x16x32_bf16 v[122:125], v[152:155], v[176:179], v[122:125]
	v_mfma_f32_16x16x32_bf16 v[110:113], v[140:143], v[188:191], v[110:113]
	v_mfma_f32_16x16x32_bf16 v[106:109], v[152:155], v[188:191], v[106:109]
	v_mfma_f32_16x16x32_bf16 v[94:97], v[140:143], v[210:213], v[94:97]
	v_mfma_f32_16x16x32_bf16 v[90:93], v[152:155], v[210:213], v[90:93]
	v_mfma_f32_16x16x32_bf16 v[78:81], v[140:143], v[218:221], v[78:81]
	v_mfma_f32_16x16x32_bf16 v[74:77], v[152:155], v[218:221], v[74:77]
	v_mfma_f32_16x16x32_bf16 v[126:129], v[148:151], v[184:187], v[126:129]
	v_mfma_f32_16x16x32_bf16 v[122:125], v[156:159], v[184:187], v[122:125]
	v_mfma_f32_16x16x32_bf16 v[110:113], v[148:151], v[196:199], v[110:113]
	v_mfma_f32_16x16x32_bf16 v[106:109], v[156:159], v[196:199], v[106:109]
	v_mfma_f32_16x16x32_bf16 v[94:97], v[148:151], v[214:217], v[94:97]
	v_mfma_f32_16x16x32_bf16 v[90:93], v[156:159], v[214:217], v[90:93]
	v_mfma_f32_16x16x32_bf16 v[78:81], v[148:151], v[222:225], v[78:81]
	v_mfma_f32_16x16x32_bf16 v[74:77], v[156:159], v[222:225], v[74:77]
	v_mfma_f32_16x16x32_bf16 v[118:121], v[160:163], v[176:179], v[118:121]
	v_mfma_f32_16x16x32_bf16 v[114:117], v[168:171], v[176:179], v[114:117]
	v_mfma_f32_16x16x32_bf16 v[102:105], v[160:163], v[188:191], v[102:105]
	v_mfma_f32_16x16x32_bf16 v[98:101], v[168:171], v[188:191], v[98:101]
	v_mfma_f32_16x16x32_bf16 v[86:89], v[160:163], v[210:213], v[86:89]
	v_mfma_f32_16x16x32_bf16 v[82:85], v[168:171], v[210:213], v[82:85]
	v_mfma_f32_16x16x32_bf16 v[70:73], v[160:163], v[218:221], v[70:73]
	v_mfma_f32_16x16x32_bf16 v[66:69], v[168:171], v[218:221], v[66:69]
	v_mfma_f32_16x16x32_bf16 v[118:121], v[164:167], v[184:187], v[118:121]
	v_mfma_f32_16x16x32_bf16 v[114:117], v[172:175], v[184:187], v[114:117]
	v_mfma_f32_16x16x32_bf16 v[102:105], v[164:167], v[196:199], v[102:105]
	v_mfma_f32_16x16x32_bf16 v[98:101], v[172:175], v[196:199], v[98:101]
	v_mfma_f32_16x16x32_bf16 v[86:89], v[164:167], v[214:217], v[86:89]
	v_mfma_f32_16x16x32_bf16 v[82:85], v[172:175], v[214:217], v[82:85]
	v_mfma_f32_16x16x32_bf16 v[70:73], v[164:167], v[222:225], v[70:73]
	v_mfma_f32_16x16x32_bf16 v[66:69], v[172:175], v[222:225], v[66:69]
	s_barrier
	s_add_i32 s45, s45, s50
	v_lshl_add_u64 v[180:181], s[30:31], 0, v[0:1]
	s_mov_b32 m0, s45
	ds_read_b128 v[176:179], v147 offset:16384
	ds_read_b128 v[184:187], v147 offset:17408
	ds_read_b128 v[188:191], v147 offset:18432
	ds_read_b128 v[196:199], v147 offset:19456
	ds_read_b128 v[210:213], v147 offset:20480
	ds_read_b128 v[214:217], v147 offset:21504
	ds_read_b128 v[218:221], v147 offset:22528
	ds_read_b128 v[222:225], v147 offset:23552
	global_load_lds_dwordx4 v[180:181], off
	s_add_i32 m0, s45, 0x2000
	s_add_u32 s60, s30, 0x40000
	v_lshl_add_u64 v[192:193], s[30:31], 0, v[130:131]
	s_addc_u32 s61, s31, 0
	s_add_i32 s45, s59, s50
	global_load_lds_dwordx4 v[192:193], off
	v_lshl_add_u64 v[202:203], s[60:61], 0, v[0:1]
	s_mov_b32 m0, s45
	v_lshl_add_u64 v[226:227], s[36:37], 0, v[132:133]
	global_load_lds_dwordx4 v[202:203], off
	v_lshl_add_u64 v[202:203], s[60:61], 0, v[130:131]
	s_add_i32 m0, s45, 0x2000
	s_nop 0
	global_load_lds_dwordx4 v[202:203], off
	v_lshl_add_u64 v[202:203], s[36:37], 0, v[134:135]
	s_mov_b32 m0, s51
	s_nop 0
	global_load_lds_dwordx4 v[202:203], off
	s_mov_b32 m0, s52
	s_nop 0
	global_load_lds_dwordx4 v[226:227], off
	s_waitcnt vmcnt(8)
	s_waitcnt lgkmcnt(0)
	s_barrier
	s_waitcnt lgkmcnt(0)
	v_mfma_f32_16x16x32_bf16 v[62:65], v[140:143], v[176:179], v[62:65]
	v_mfma_f32_16x16x32_bf16 v[58:61], v[152:155], v[176:179], v[58:61]
	v_mfma_f32_16x16x32_bf16 v[46:49], v[140:143], v[188:191], v[46:49]
	v_mfma_f32_16x16x32_bf16 v[42:45], v[152:155], v[188:191], v[42:45]
	v_mfma_f32_16x16x32_bf16 v[30:33], v[140:143], v[210:213], v[30:33]
	v_mfma_f32_16x16x32_bf16 v[26:29], v[152:155], v[210:213], v[26:29]
	v_mfma_f32_16x16x32_bf16 v[14:17], v[140:143], v[218:221], v[14:17]
	v_mfma_f32_16x16x32_bf16 v[10:13], v[152:155], v[218:221], v[10:13]
	v_mfma_f32_16x16x32_bf16 v[62:65], v[148:151], v[184:187], v[62:65]
	v_mfma_f32_16x16x32_bf16 v[58:61], v[156:159], v[184:187], v[58:61]
	v_mfma_f32_16x16x32_bf16 v[46:49], v[148:151], v[196:199], v[46:49]
	v_mfma_f32_16x16x32_bf16 v[42:45], v[156:159], v[196:199], v[42:45]
	v_mfma_f32_16x16x32_bf16 v[30:33], v[148:151], v[214:217], v[30:33]
	v_mfma_f32_16x16x32_bf16 v[26:29], v[156:159], v[214:217], v[26:29]
	v_mfma_f32_16x16x32_bf16 v[14:17], v[148:151], v[222:225], v[14:17]
	v_mfma_f32_16x16x32_bf16 v[10:13], v[156:159], v[222:225], v[10:13]
	v_mfma_f32_16x16x32_bf16 v[54:57], v[160:163], v[176:179], v[54:57]
	v_mfma_f32_16x16x32_bf16 v[50:53], v[168:171], v[176:179], v[50:53]
	v_mfma_f32_16x16x32_bf16 v[38:41], v[160:163], v[188:191], v[38:41]
	v_mfma_f32_16x16x32_bf16 v[34:37], v[168:171], v[188:191], v[34:37]
	v_mfma_f32_16x16x32_bf16 v[22:25], v[160:163], v[210:213], v[22:25]
	v_mfma_f32_16x16x32_bf16 v[18:21], v[168:171], v[210:213], v[18:21]
	v_mfma_f32_16x16x32_bf16 v[6:9], v[160:163], v[218:221], v[6:9]
	v_mfma_f32_16x16x32_bf16 v[2:5], v[168:171], v[218:221], v[2:5]
	v_mfma_f32_16x16x32_bf16 v[54:57], v[164:167], v[184:187], v[54:57]
	v_mfma_f32_16x16x32_bf16 v[50:53], v[172:175], v[184:187], v[50:53]
	v_mfma_f32_16x16x32_bf16 v[38:41], v[164:167], v[196:199], v[38:41]
	v_mfma_f32_16x16x32_bf16 v[34:37], v[172:175], v[196:199], v[34:37]
	v_mfma_f32_16x16x32_bf16 v[22:25], v[164:167], v[214:217], v[22:25]
	v_mfma_f32_16x16x32_bf16 v[18:21], v[172:175], v[214:217], v[18:21]
	v_mfma_f32_16x16x32_bf16 v[6:9], v[164:167], v[222:225], v[6:9]
	v_mfma_f32_16x16x32_bf16 v[2:5], v[172:175], v[222:225], v[2:5]
	s_barrier
	s_add_i32 s45, 0, 0x18000
	s_add_i32 s59, 0, 0x1c000
	v_add_u32_e32 v156, s45, v145
	v_add_u32_e32 v172, s59, v145
	ds_read_b128 v[140:143], v156
	ds_read_b128 v[148:151], v156 offset:1024
	ds_read_b128 v[152:155], v156 offset:2048
	ds_read_b128 v[156:159], v156 offset:3072
	ds_read_b128 v[160:163], v172
	ds_read_b128 v[164:167], v172 offset:1024
	ds_read_b128 v[168:171], v172 offset:2048
	ds_read_b128 v[172:175], v172 offset:3072
	s_add_u32 s36, s36, 0x40000
	s_addc_u32 s37, s37, 0
	s_mov_b32 m0, s53
	v_lshl_add_u64 v[228:229], s[36:37], 0, v[134:135]
	ds_read_b128 v[176:179], v147 offset:32768
	ds_read_b128 v[184:187], v147 offset:33792
	ds_read_b128 v[188:191], v147 offset:34816
	ds_read_b128 v[196:199], v147 offset:35840
	ds_read_b128 v[210:213], v147 offset:36864
	ds_read_b128 v[214:217], v147 offset:37888
	ds_read_b128 v[218:221], v147 offset:38912
	ds_read_b128 v[222:225], v147 offset:39936
	global_load_lds_dwordx4 v[228:229], off
	v_lshl_add_u64 v[228:229], s[36:37], 0, v[132:133]
	s_mov_b32 m0, s54
	s_nop 0
	global_load_lds_dwordx4 v[228:229], off
	s_waitcnt vmcnt(8)
	s_waitcnt lgkmcnt(0)
	s_barrier
	s_waitcnt lgkmcnt(0)
	v_mfma_f32_16x16x32_bf16 v[126:129], v[140:143], v[176:179], v[126:129]
	v_mfma_f32_16x16x32_bf16 v[122:125], v[152:155], v[176:179], v[122:125]
	v_mfma_f32_16x16x32_bf16 v[110:113], v[140:143], v[188:191], v[110:113]
	v_mfma_f32_16x16x32_bf16 v[106:109], v[152:155], v[188:191], v[106:109]
	v_mfma_f32_16x16x32_bf16 v[94:97], v[140:143], v[210:213], v[94:97]
	v_mfma_f32_16x16x32_bf16 v[90:93], v[152:155], v[210:213], v[90:93]
	v_mfma_f32_16x16x32_bf16 v[78:81], v[140:143], v[218:221], v[78:81]
	v_mfma_f32_16x16x32_bf16 v[74:77], v[152:155], v[218:221], v[74:77]
	v_mfma_f32_16x16x32_bf16 v[126:129], v[148:151], v[184:187], v[126:129]
	v_mfma_f32_16x16x32_bf16 v[122:125], v[156:159], v[184:187], v[122:125]
	v_mfma_f32_16x16x32_bf16 v[110:113], v[148:151], v[196:199], v[110:113]
	v_mfma_f32_16x16x32_bf16 v[106:109], v[156:159], v[196:199], v[106:109]
	v_mfma_f32_16x16x32_bf16 v[94:97], v[148:151], v[214:217], v[94:97]
	v_mfma_f32_16x16x32_bf16 v[90:93], v[156:159], v[214:217], v[90:93]
	v_mfma_f32_16x16x32_bf16 v[78:81], v[148:151], v[222:225], v[78:81]
	v_mfma_f32_16x16x32_bf16 v[74:77], v[156:159], v[222:225], v[74:77]
	v_mfma_f32_16x16x32_bf16 v[118:121], v[160:163], v[176:179], v[118:121]
	v_mfma_f32_16x16x32_bf16 v[114:117], v[168:171], v[176:179], v[114:117]
	v_mfma_f32_16x16x32_bf16 v[102:105], v[160:163], v[188:191], v[102:105]
	v_mfma_f32_16x16x32_bf16 v[98:101], v[168:171], v[188:191], v[98:101]
	v_mfma_f32_16x16x32_bf16 v[86:89], v[160:163], v[210:213], v[86:89]
	v_mfma_f32_16x16x32_bf16 v[82:85], v[168:171], v[210:213], v[82:85]
	v_mfma_f32_16x16x32_bf16 v[70:73], v[160:163], v[218:221], v[70:73]
	v_mfma_f32_16x16x32_bf16 v[66:69], v[168:171], v[218:221], v[66:69]
	v_mfma_f32_16x16x32_bf16 v[118:121], v[164:167], v[184:187], v[118:121]
	v_mfma_f32_16x16x32_bf16 v[114:117], v[172:175], v[184:187], v[114:117]
	v_mfma_f32_16x16x32_bf16 v[102:105], v[164:167], v[196:199], v[102:105]
	v_mfma_f32_16x16x32_bf16 v[98:101], v[172:175], v[196:199], v[98:101]
	v_mfma_f32_16x16x32_bf16 v[86:89], v[164:167], v[214:217], v[86:89]
	v_mfma_f32_16x16x32_bf16 v[82:85], v[172:175], v[214:217], v[82:85]
	v_mfma_f32_16x16x32_bf16 v[70:73], v[164:167], v[222:225], v[70:73]
	v_mfma_f32_16x16x32_bf16 v[66:69], v[172:175], v[222:225], v[66:69]
	s_barrier
	s_add_i32 s36, s45, s50
	v_lshl_add_u64 v[180:181], v[180:181], 0, s[22:23]
	s_mov_b32 m0, s36
	ds_read_b128 v[176:179], v147 offset:49152
	ds_read_b128 v[184:187], v147 offset:50176
	ds_read_b128 v[188:191], v147 offset:51200
	ds_read_b128 v[196:199], v147 offset:52224
	ds_read_b128 v[210:213], v147 offset:53248
	ds_read_b128 v[214:217], v147 offset:54272
	ds_read_b128 v[218:221], v147 offset:55296
	ds_read_b128 v[222:225], v147 offset:56320
	global_load_lds_dwordx4 v[180:181], off
	s_add_i32 m0, s36, 0x2000
	s_add_u32 s30, s30, 0x40080
	v_lshl_add_u64 v[180:181], v[192:193], 0, s[22:23]
	s_addc_u32 s31, s31, 0
	s_add_i32 s36, s59, s50
	global_load_lds_dwordx4 v[180:181], off
	v_lshl_add_u64 v[180:181], s[30:31], 0, v[0:1]
	s_mov_b32 m0, s36
	s_nop 0
	global_load_lds_dwordx4 v[180:181], off
	v_lshl_add_u64 v[180:181], s[30:31], 0, v[130:131]
	s_add_i32 m0, s36, 0x2000
	s_nop 0
	global_load_lds_dwordx4 v[180:181], off
	v_lshl_add_u64 v[180:181], v[202:203], 0, s[22:23]
	s_mov_b32 m0, s56
	s_nop 0
	global_load_lds_dwordx4 v[180:181], off
	v_lshl_add_u64 v[180:181], v[226:227], 0, s[22:23]
	s_mov_b32 m0, s57
	s_nop 0
	global_load_lds_dwordx4 v[180:181], off
	s_waitcnt vmcnt(8)
	s_waitcnt lgkmcnt(0)
	s_barrier
	s_waitcnt lgkmcnt(0)
	v_mfma_f32_16x16x32_bf16 v[62:65], v[140:143], v[176:179], v[62:65]
	v_mfma_f32_16x16x32_bf16 v[58:61], v[152:155], v[176:179], v[58:61]
	v_mfma_f32_16x16x32_bf16 v[46:49], v[140:143], v[188:191], v[46:49]
	v_mfma_f32_16x16x32_bf16 v[42:45], v[152:155], v[188:191], v[42:45]
	v_mfma_f32_16x16x32_bf16 v[30:33], v[140:143], v[210:213], v[30:33]
	v_mfma_f32_16x16x32_bf16 v[26:29], v[152:155], v[210:213], v[26:29]
	v_mfma_f32_16x16x32_bf16 v[14:17], v[140:143], v[218:221], v[14:17]
	v_mfma_f32_16x16x32_bf16 v[10:13], v[152:155], v[218:221], v[10:13]
	v_mfma_f32_16x16x32_bf16 v[62:65], v[148:151], v[184:187], v[62:65]
	v_mfma_f32_16x16x32_bf16 v[58:61], v[156:159], v[184:187], v[58:61]
	v_mfma_f32_16x16x32_bf16 v[46:49], v[148:151], v[196:199], v[46:49]
	v_mfma_f32_16x16x32_bf16 v[42:45], v[156:159], v[196:199], v[42:45]
	v_mfma_f32_16x16x32_bf16 v[30:33], v[148:151], v[214:217], v[30:33]
	v_mfma_f32_16x16x32_bf16 v[26:29], v[156:159], v[214:217], v[26:29]
	v_mfma_f32_16x16x32_bf16 v[14:17], v[148:151], v[222:225], v[14:17]
	v_mfma_f32_16x16x32_bf16 v[10:13], v[156:159], v[222:225], v[10:13]
	v_mfma_f32_16x16x32_bf16 v[54:57], v[160:163], v[176:179], v[54:57]
	v_mfma_f32_16x16x32_bf16 v[50:53], v[168:171], v[176:179], v[50:53]
	v_mfma_f32_16x16x32_bf16 v[38:41], v[160:163], v[188:191], v[38:41]
	v_mfma_f32_16x16x32_bf16 v[34:37], v[168:171], v[188:191], v[34:37]
	v_mfma_f32_16x16x32_bf16 v[22:25], v[160:163], v[210:213], v[22:25]
	v_mfma_f32_16x16x32_bf16 v[18:21], v[168:171], v[210:213], v[18:21]
	v_mfma_f32_16x16x32_bf16 v[6:9], v[160:163], v[218:221], v[6:9]
	v_mfma_f32_16x16x32_bf16 v[2:5], v[168:171], v[218:221], v[2:5]
	v_mfma_f32_16x16x32_bf16 v[54:57], v[164:167], v[184:187], v[54:57]
	v_mfma_f32_16x16x32_bf16 v[50:53], v[172:175], v[184:187], v[50:53]
	v_mfma_f32_16x16x32_bf16 v[38:41], v[164:167], v[196:199], v[38:41]
	v_mfma_f32_16x16x32_bf16 v[34:37], v[172:175], v[196:199], v[34:37]
	v_mfma_f32_16x16x32_bf16 v[22:25], v[164:167], v[214:217], v[22:25]
	v_mfma_f32_16x16x32_bf16 v[18:21], v[172:175], v[214:217], v[18:21]
	v_mfma_f32_16x16x32_bf16 v[6:9], v[164:167], v[222:225], v[6:9]
	v_mfma_f32_16x16x32_bf16 v[2:5], v[172:175], v[222:225], v[2:5]
	s_barrier
	s_add_i32 s35, s35, 2
	s_add_u32 s12, s12, 0x100
	s_addc_u32 s13, s13, 0
	s_add_u32 s26, s26, 0x100
	s_addc_u32 s28, s28, 0
	s_cmp_gt_u32 s35, 13
	s_cbranch_scc0 .LBB0_695
	s_and_b64 vcc, exec, s[20:21]
	s_cbranch_vccz .LBB0_698
	s_barrier

.Lsprio_2:
.LBB0_792:
	s_add_u32 s36, s34, 0xfffc0080
	s_addc_u32 s37, s35, -1
	s_add_i32 s51, 0, 0x10000
	s_cmp_eq_u32 s50, 12
	s_cselect_b32 s41, s15, s37
	s_cselect_b32 s40, s46, s36
	v_add_u32_e32 v149, s51, v145
	s_cselect_b32 s37, s13, s49
	s_cselect_b32 s36, s47, s48
	s_add_i32 s54, 0, 0x14000
	ds_read_b128 v[140:143], v149
	ds_read_b128 v[150:153], v149 offset:1024
	ds_read_b128 v[154:157], v149 offset:2048
	ds_read_b128 v[158:161], v149 offset:3072
	v_add_u32_e32 v149, s54, v145
	ds_read_b128 v[162:165], v149
	ds_read_b128 v[166:169], v149 offset:1024
	ds_read_b128 v[170:173], v149 offset:2048
	ds_read_b128 v[174:177], v149 offset:3072
	v_lshl_add_u64 v[192:193], s[34:35], 0, v[136:137]
	s_add_i32 m0, s18, 0xc000
	ds_read_b128 v[178:181], v148
	ds_read_b128 v[184:187], v148 offset:1024
	ds_read_b128 v[188:191], v148 offset:2048
	ds_read_b128 v[196:199], v148 offset:3072
	ds_read_b128 v[210:213], v148 offset:4096
	ds_read_b128 v[214:217], v148 offset:5120
	ds_read_b128 v[218:221], v148 offset:6144
	ds_read_b128 v[222:225], v148 offset:7168
	global_load_lds_dwordx4 v[192:193], off
	v_lshl_add_u64 v[192:193], s[34:35], 0, v[138:139]
	s_add_i32 m0, s18, 0xe000
	s_nop 0
	global_load_lds_dwordx4 v[192:193], off
	s_waitcnt vmcnt(8)
	s_waitcnt lgkmcnt(0)
	s_barrier
	s_waitcnt lgkmcnt(0)
	v_mfma_f32_16x16x32_bf16 v[126:129], v[140:143], v[178:181], v[126:129]
	v_mfma_f32_16x16x32_bf16 v[122:125], v[154:157], v[178:181], v[122:125]
	v_mfma_f32_16x16x32_bf16 v[110:113], v[140:143], v[188:191], v[110:113]
	v_mfma_f32_16x16x32_bf16 v[106:109], v[154:157], v[188:191], v[106:109]
	v_mfma_f32_16x16x32_bf16 v[94:97], v[140:143], v[210:213], v[94:97]
	v_mfma_f32_16x16x32_bf16 v[90:93], v[154:157], v[210:213], v[90:93]
	v_mfma_f32_16x16x32_bf16 v[78:81], v[140:143], v[218:221], v[78:81]
	v_mfma_f32_16x16x32_bf16 v[74:77], v[154:157], v[218:221], v[74:77]
	v_mfma_f32_16x16x32_bf16 v[126:129], v[150:153], v[184:187], v[126:129]
	v_mfma_f32_16x16x32_bf16 v[122:125], v[158:161], v[184:187], v[122:125]
	v_mfma_f32_16x16x32_bf16 v[110:113], v[150:153], v[196:199], v[110:113]
	v_mfma_f32_16x16x32_bf16 v[106:109], v[158:161], v[196:199], v[106:109]
	v_mfma_f32_16x16x32_bf16 v[94:97], v[150:153], v[214:217], v[94:97]
	v_mfma_f32_16x16x32_bf16 v[90:93], v[158:161], v[214:217], v[90:93]
	v_mfma_f32_16x16x32_bf16 v[78:81], v[150:153], v[222:225], v[78:81]
	v_mfma_f32_16x16x32_bf16 v[74:77], v[158:161], v[222:225], v[74:77]
	v_mfma_f32_16x16x32_bf16 v[118:121], v[162:165], v[178:181], v[118:121]
	v_mfma_f32_16x16x32_bf16 v[114:117], v[170:173], v[178:181], v[114:117]
	v_mfma_f32_16x16x32_bf16 v[102:105], v[162:165], v[188:191], v[102:105]
	v_mfma_f32_16x16x32_bf16 v[98:101], v[170:173], v[188:191], v[98:101]
	v_mfma_f32_16x16x32_bf16 v[86:89], v[162:165], v[210:213], v[86:89]
	v_mfma_f32_16x16x32_bf16 v[82:85], v[170:173], v[210:213], v[82:85]
	v_mfma_f32_16x16x32_bf16 v[70:73], v[162:165], v[218:221], v[70:73]
	v_mfma_f32_16x16x32_bf16 v[66:69], v[170:173], v[218:221], v[66:69]
	v_mfma_f32_16x16x32_bf16 v[118:121], v[166:169], v[184:187], v[118:121]
	v_mfma_f32_16x16x32_bf16 v[114:117], v[174:177], v[184:187], v[114:117]
	v_mfma_f32_16x16x32_bf16 v[102:105], v[166:169], v[196:199], v[102:105]
	v_mfma_f32_16x16x32_bf16 v[98:101], v[174:177], v[196:199], v[98:101]
	v_mfma_f32_16x16x32_bf16 v[86:89], v[166:169], v[214:217], v[86:89]
	v_mfma_f32_16x16x32_bf16 v[82:85], v[174:177], v[214:217], v[82:85]
	v_mfma_f32_16x16x32_bf16 v[70:73], v[166:169], v[222:225], v[70:73]
	v_mfma_f32_16x16x32_bf16 v[66:69], v[174:177], v[222:225], v[66:69]
	s_barrier
	s_add_i32 s51, s51, s0
	v_lshl_add_u64 v[192:193], s[36:37], 0, v[0:1]
	s_mov_b32 m0, s51
	ds_read_b128 v[178:181], v148 offset:16384
	ds_read_b128 v[184:187], v148 offset:17408
	ds_read_b128 v[188:191], v148 offset:18432
	ds_read_b128 v[196:199], v148 offset:19456
	ds_read_b128 v[210:213], v148 offset:20480
	ds_read_b128 v[214:217], v148 offset:21504
	ds_read_b128 v[218:221], v148 offset:22528
	ds_read_b128 v[222:225], v148 offset:23552
	global_load_lds_dwordx4 v[192:193], off
	s_add_i32 m0, s51, 0x2000
	s_add_u32 s52, s36, 0x40000
	v_lshl_add_u64 v[202:203], s[36:37], 0, v[130:131]
	s_addc_u32 s53, s37, 0
	s_add_i32 s51, s54, s0
	global_load_lds_dwordx4 v[202:203], off
	v_lshl_add_u64 v[226:227], s[52:53], 0, v[0:1]
	s_mov_b32 m0, s51
	v_lshl_add_u64 v[228:229], s[40:41], 0, v[132:133]
	global_load_lds_dwordx4 v[226:227], off
	v_lshl_add_u64 v[226:227], s[52:53], 0, v[130:131]
	s_add_i32 m0, s51, 0x2000
	s_nop 0
	global_load_lds_dwordx4 v[226:227], off
	v_lshl_add_u64 v[226:227], s[40:41], 0, v[134:135]
	s_mov_b32 m0, s18
	s_nop 0
	global_load_lds_dwordx4 v[226:227], off
	s_mov_b32 m0, s19
	s_nop 0
	global_load_lds_dwordx4 v[228:229], off
	s_waitcnt vmcnt(8)
	s_waitcnt lgkmcnt(0)
	s_barrier
	s_waitcnt lgkmcnt(0)
	v_mfma_f32_16x16x32_bf16 v[62:65], v[140:143], v[178:181], v[62:65]
	v_mfma_f32_16x16x32_bf16 v[58:61], v[154:157], v[178:181], v[58:61]
	v_mfma_f32_16x16x32_bf16 v[46:49], v[140:143], v[188:191], v[46:49]
	v_mfma_f32_16x16x32_bf16 v[42:45], v[154:157], v[188:191], v[42:45]
	v_mfma_f32_16x16x32_bf16 v[30:33], v[140:143], v[210:213], v[30:33]
	v_mfma_f32_16x16x32_bf16 v[26:29], v[154:157], v[210:213], v[26:29]
	v_mfma_f32_16x16x32_bf16 v[14:17], v[140:143], v[218:221], v[14:17]
	v_mfma_f32_16x16x32_bf16 v[10:13], v[154:157], v[218:221], v[10:13]
	v_mfma_f32_16x16x32_bf16 v[62:65], v[150:153], v[184:187], v[62:65]
	v_mfma_f32_16x16x32_bf16 v[58:61], v[158:161], v[184:187], v[58:61]
	v_mfma_f32_16x16x32_bf16 v[46:49], v[150:153], v[196:199], v[46:49]
	v_mfma_f32_16x16x32_bf16 v[42:45], v[158:161], v[196:199], v[42:45]
	v_mfma_f32_16x16x32_bf16 v[30:33], v[150:153], v[214:217], v[30:33]
	v_mfma_f32_16x16x32_bf16 v[26:29], v[158:161], v[214:217], v[26:29]
	v_mfma_f32_16x16x32_bf16 v[14:17], v[150:153], v[222:225], v[14:17]
	v_mfma_f32_16x16x32_bf16 v[10:13], v[158:161], v[222:225], v[10:13]
	v_mfma_f32_16x16x32_bf16 v[54:57], v[162:165], v[178:181], v[54:57]
	v_mfma_f32_16x16x32_bf16 v[50:53], v[170:173], v[178:181], v[50:53]
	v_mfma_f32_16x16x32_bf16 v[38:41], v[162:165], v[188:191], v[38:41]
	v_mfma_f32_16x16x32_bf16 v[34:37], v[170:173], v[188:191], v[34:37]
	v_mfma_f32_16x16x32_bf16 v[22:25], v[162:165], v[210:213], v[22:25]
	v_mfma_f32_16x16x32_bf16 v[18:21], v[170:173], v[210:213], v[18:21]
	v_mfma_f32_16x16x32_bf16 v[6:9], v[162:165], v[218:221], v[6:9]
	v_mfma_f32_16x16x32_bf16 v[2:5], v[170:173], v[218:221], v[2:5]
	v_mfma_f32_16x16x32_bf16 v[54:57], v[166:169], v[184:187], v[54:57]
	v_mfma_f32_16x16x32_bf16 v[50:53], v[174:177], v[184:187], v[50:53]
	v_mfma_f32_16x16x32_bf16 v[38:41], v[166:169], v[196:199], v[38:41]
	v_mfma_f32_16x16x32_bf16 v[34:37], v[174:177], v[196:199], v[34:37]
	v_mfma_f32_16x16x32_bf16 v[22:25], v[166:169], v[214:217], v[22:25]
	v_mfma_f32_16x16x32_bf16 v[18:21], v[174:177], v[214:217], v[18:21]
	v_mfma_f32_16x16x32_bf16 v[6:9], v[166:169], v[222:225], v[6:9]
	v_mfma_f32_16x16x32_bf16 v[2:5], v[174:177], v[222:225], v[2:5]
	s_barrier
	s_add_i32 s51, 0, 0x18000
	v_add_u32_e32 v149, s51, v145
	s_add_i32 s52, 0, 0x1c000
	ds_read_b128 v[140:143], v149
	ds_read_b128 v[150:153], v149 offset:1024
	ds_read_b128 v[154:157], v149 offset:2048
	ds_read_b128 v[158:161], v149 offset:3072
	v_add_u32_e32 v149, s52, v145
	ds_read_b128 v[162:165], v149
	ds_read_b128 v[166:169], v149 offset:1024
	ds_read_b128 v[170:173], v149 offset:2048
	ds_read_b128 v[174:177], v149 offset:3072
	s_add_u32 s40, s40, 0x40000
	s_addc_u32 s41, s41, 0
	s_mov_b32 m0, s24
	v_lshl_add_u64 v[230:231], s[40:41], 0, v[134:135]
	ds_read_b128 v[178:181], v148 offset:32768
	ds_read_b128 v[184:187], v148 offset:33792
	ds_read_b128 v[188:191], v148 offset:34816
	ds_read_b128 v[196:199], v148 offset:35840
	ds_read_b128 v[210:213], v148 offset:36864
	ds_read_b128 v[214:217], v148 offset:37888
	ds_read_b128 v[218:221], v148 offset:38912
	ds_read_b128 v[222:225], v148 offset:39936
	global_load_lds_dwordx4 v[230:231], off
	v_lshl_add_u64 v[230:231], s[40:41], 0, v[132:133]
	s_mov_b32 m0, s25
	s_nop 0
	global_load_lds_dwordx4 v[230:231], off
	s_waitcnt vmcnt(8)
	s_waitcnt lgkmcnt(0)
	s_barrier
	s_waitcnt lgkmcnt(0)
	v_mfma_f32_16x16x32_bf16 v[126:129], v[140:143], v[178:181], v[126:129]
	v_mfma_f32_16x16x32_bf16 v[122:125], v[154:157], v[178:181], v[122:125]
	v_mfma_f32_16x16x32_bf16 v[110:113], v[140:143], v[188:191], v[110:113]
	v_mfma_f32_16x16x32_bf16 v[106:109], v[154:157], v[188:191], v[106:109]
	v_mfma_f32_16x16x32_bf16 v[94:97], v[140:143], v[210:213], v[94:97]
	v_mfma_f32_16x16x32_bf16 v[90:93], v[154:157], v[210:213], v[90:93]
	v_mfma_f32_16x16x32_bf16 v[78:81], v[140:143], v[218:221], v[78:81]
	v_mfma_f32_16x16x32_bf16 v[74:77], v[154:157], v[218:221], v[74:77]
	v_mfma_f32_16x16x32_bf16 v[126:129], v[150:153], v[184:187], v[126:129]
	v_mfma_f32_16x16x32_bf16 v[122:125], v[158:161], v[184:187], v[122:125]
	v_mfma_f32_16x16x32_bf16 v[110:113], v[150:153], v[196:199], v[110:113]
	v_mfma_f32_16x16x32_bf16 v[106:109], v[158:161], v[196:199], v[106:109]
	v_mfma_f32_16x16x32_bf16 v[94:97], v[150:153], v[214:217], v[94:97]
	v_mfma_f32_16x16x32_bf16 v[90:93], v[158:161], v[214:217], v[90:93]
	v_mfma_f32_16x16x32_bf16 v[78:81], v[150:153], v[222:225], v[78:81]
	v_mfma_f32_16x16x32_bf16 v[74:77], v[158:161], v[222:225], v[74:77]
	v_mfma_f32_16x16x32_bf16 v[118:121], v[162:165], v[178:181], v[118:121]
	v_mfma_f32_16x16x32_bf16 v[114:117], v[170:173], v[178:181], v[114:117]
	v_mfma_f32_16x16x32_bf16 v[102:105], v[162:165], v[188:191], v[102:105]
	v_mfma_f32_16x16x32_bf16 v[98:101], v[170:173], v[188:191], v[98:101]
	v_mfma_f32_16x16x32_bf16 v[86:89], v[162:165], v[210:213], v[86:89]
	v_mfma_f32_16x16x32_bf16 v[82:85], v[170:173], v[210:213], v[82:85]
	v_mfma_f32_16x16x32_bf16 v[70:73], v[162:165], v[218:221], v[70:73]
	v_mfma_f32_16x16x32_bf16 v[66:69], v[170:173], v[218:221], v[66:69]
	v_mfma_f32_16x16x32_bf16 v[118:121], v[166:169], v[184:187], v[118:121]
	v_mfma_f32_16x16x32_bf16 v[114:117], v[174:177], v[184:187], v[114:117]
	v_mfma_f32_16x16x32_bf16 v[102:105], v[166:169], v[196:199], v[102:105]
	v_mfma_f32_16x16x32_bf16 v[98:101], v[174:177], v[196:199], v[98:101]
	v_mfma_f32_16x16x32_bf16 v[86:89], v[166:169], v[214:217], v[86:89]
	v_mfma_f32_16x16x32_bf16 v[82:85], v[174:177], v[214:217], v[82:85]
	v_mfma_f32_16x16x32_bf16 v[70:73], v[166:169], v[222:225], v[70:73]
	v_mfma_f32_16x16x32_bf16 v[66:69], v[174:177], v[222:225], v[66:69]
	s_barrier
	s_add_i32 s40, s51, s0
	v_lshl_add_u64 v[192:193], v[192:193], 0, s[22:23]
	s_mov_b32 m0, s40
	ds_read_b128 v[178:181], v148 offset:49152
	ds_read_b128 v[184:187], v148 offset:50176
	ds_read_b128 v[188:191], v148 offset:51200
	ds_read_b128 v[196:199], v148 offset:52224
	ds_read_b128 v[210:213], v148 offset:53248
	ds_read_b128 v[214:217], v148 offset:54272
	ds_read_b128 v[218:221], v148 offset:55296
	ds_read_b128 v[222:225], v148 offset:56320
	global_load_lds_dwordx4 v[192:193], off
	s_add_i32 m0, s40, 0x2000
	s_add_u32 s36, s36, 0x40080
	v_lshl_add_u64 v[192:193], v[202:203], 0, s[22:23]
	s_addc_u32 s37, s37, 0
	s_add_i32 s40, s52, s0
	global_load_lds_dwordx4 v[192:193], off
	v_lshl_add_u64 v[192:193], s[36:37], 0, v[0:1]
	s_mov_b32 m0, s40
	s_nop 0
	global_load_lds_dwordx4 v[192:193], off
	v_lshl_add_u64 v[192:193], s[36:37], 0, v[130:131]
	s_add_i32 m0, s40, 0x2000
	s_nop 0
	global_load_lds_dwordx4 v[192:193], off
	v_lshl_add_u64 v[192:193], v[226:227], 0, s[22:23]
	s_mov_b32 m0, s26
	s_nop 0
	global_load_lds_dwordx4 v[192:193], off
	v_lshl_add_u64 v[192:193], v[228:229], 0, s[22:23]
	s_mov_b32 m0, s28
	s_nop 0
	global_load_lds_dwordx4 v[192:193], off
	s_waitcnt vmcnt(8)
	s_waitcnt lgkmcnt(0)
	s_barrier
	s_waitcnt lgkmcnt(0)
	v_mfma_f32_16x16x32_bf16 v[62:65], v[140:143], v[178:181], v[62:65]
	v_mfma_f32_16x16x32_bf16 v[58:61], v[154:157], v[178:181], v[58:61]
	v_mfma_f32_16x16x32_bf16 v[46:49], v[140:143], v[188:191], v[46:49]
	v_mfma_f32_16x16x32_bf16 v[42:45], v[154:157], v[188:191], v[42:45]
	v_mfma_f32_16x16x32_bf16 v[30:33], v[140:143], v[210:213], v[30:33]
	v_mfma_f32_16x16x32_bf16 v[26:29], v[154:157], v[210:213], v[26:29]
	v_mfma_f32_16x16x32_bf16 v[14:17], v[140:143], v[218:221], v[14:17]
	v_mfma_f32_16x16x32_bf16 v[10:13], v[154:157], v[218:221], v[10:13]
	v_mfma_f32_16x16x32_bf16 v[62:65], v[150:153], v[184:187], v[62:65]
	v_mfma_f32_16x16x32_bf16 v[58:61], v[158:161], v[184:187], v[58:61]
	v_mfma_f32_16x16x32_bf16 v[46:49], v[150:153], v[196:199], v[46:49]
	v_mfma_f32_16x16x32_bf16 v[42:45], v[158:161], v[196:199], v[42:45]
	v_mfma_f32_16x16x32_bf16 v[30:33], v[150:153], v[214:217], v[30:33]
	v_mfma_f32_16x16x32_bf16 v[26:29], v[158:161], v[214:217], v[26:29]
	v_mfma_f32_16x16x32_bf16 v[14:17], v[150:153], v[222:225], v[14:17]
	v_mfma_f32_16x16x32_bf16 v[10:13], v[158:161], v[222:225], v[10:13]
	v_mfma_f32_16x16x32_bf16 v[54:57], v[162:165], v[178:181], v[54:57]
	v_mfma_f32_16x16x32_bf16 v[50:53], v[170:173], v[178:181], v[50:53]
	v_mfma_f32_16x16x32_bf16 v[38:41], v[162:165], v[188:191], v[38:41]
	v_mfma_f32_16x16x32_bf16 v[34:37], v[170:173], v[188:191], v[34:37]
	v_mfma_f32_16x16x32_bf16 v[22:25], v[162:165], v[210:213], v[22:25]
	v_mfma_f32_16x16x32_bf16 v[18:21], v[170:173], v[210:213], v[18:21]
	v_mfma_f32_16x16x32_bf16 v[6:9], v[162:165], v[218:221], v[6:9]
	v_mfma_f32_16x16x32_bf16 v[2:5], v[170:173], v[218:221], v[2:5]
	v_mfma_f32_16x16x32_bf16 v[54:57], v[166:169], v[184:187], v[54:57]
	v_mfma_f32_16x16x32_bf16 v[50:53], v[174:177], v[184:187], v[50:53]
	v_mfma_f32_16x16x32_bf16 v[38:41], v[166:169], v[196:199], v[38:41]
	v_mfma_f32_16x16x32_bf16 v[34:37], v[174:177], v[196:199], v[34:37]
	v_mfma_f32_16x16x32_bf16 v[22:25], v[166:169], v[214:217], v[22:25]
	v_mfma_f32_16x16x32_bf16 v[18:21], v[174:177], v[214:217], v[18:21]
	v_mfma_f32_16x16x32_bf16 v[6:9], v[166:169], v[222:225], v[6:9]
	v_mfma_f32_16x16x32_bf16 v[2:5], v[174:177], v[222:225], v[2:5]
	s_barrier
	s_add_i32 s50, s50, 2
	s_add_u32 s34, s34, 0x100
	s_addc_u32 s35, s35, 0
	s_add_u32 s48, s48, 0x100
	s_addc_u32 s49, s49, 0
	s_cmp_gt_u32 s50, 13
	s_cbranch_scc0 .LBB0_792
	s_and_b64 vcc, exec, s[10:11]
	s_cbranch_vccz .LBB0_795
	s_barrier

.Lsprio_3:
.LBB0_864:
	s_add_u32 s30, s12, 0xfff00080
	s_addc_u32 s31, s13, -1
	s_add_i32 s45, 0, 0x10000
	s_cmp_eq_u32 s35, 60
	s_cselect_b32 s37, s3, s31
	s_cselect_b32 s36, s16, s30
	s_cselect_b32 s31, s24, s28
	s_cselect_b32 s30, s25, s26
	s_add_i32 s59, 0, 0x14000
	v_add_u32_e32 v156, s45, v145
	v_add_u32_e32 v172, s59, v145
	ds_read_b128 v[140:143], v156
	ds_read_b128 v[148:151], v156 offset:1024
	ds_read_b128 v[152:155], v156 offset:2048
	ds_read_b128 v[156:159], v156 offset:3072
	ds_read_b128 v[160:163], v172
	ds_read_b128 v[164:167], v172 offset:1024
	ds_read_b128 v[168:171], v172 offset:2048
	ds_read_b128 v[172:175], v172 offset:3072
	v_lshl_add_u64 v[180:181], s[12:13], 0, v[136:137]
	s_add_i32 m0, s51, 0xc000
	ds_read_b128 v[176:179], v147
	ds_read_b128 v[184:187], v147 offset:1024
	ds_read_b128 v[188:191], v147 offset:2048
	ds_read_b128 v[196:199], v147 offset:3072
	ds_read_b128 v[210:213], v147 offset:4096
	ds_read_b128 v[214:217], v147 offset:5120
	ds_read_b128 v[218:221], v147 offset:6144
	ds_read_b128 v[222:225], v147 offset:7168
	global_load_lds_dwordx4 v[180:181], off
	v_lshl_add_u64 v[180:181], s[12:13], 0, v[138:139]
	s_add_i32 m0, s51, 0xe000
	s_nop 0
	global_load_lds_dwordx4 v[180:181], off
	s_waitcnt vmcnt(8)
	s_waitcnt lgkmcnt(0)
	s_barrier
	s_waitcnt lgkmcnt(0)
	v_mfma_f32_16x16x32_bf16 v[126:129], v[140:143], v[176:179], v[126:129]
	v_mfma_f32_16x16x32_bf16 v[122:125], v[152:155], v[176:179], v[122:125]
	v_mfma_f32_16x16x32_bf16 v[110:113], v[140:143], v[188:191], v[110:113]
	v_mfma_f32_16x16x32_bf16 v[106:109], v[152:155], v[188:191], v[106:109]
	v_mfma_f32_16x16x32_bf16 v[94:97], v[140:143], v[210:213], v[94:97]
	v_mfma_f32_16x16x32_bf16 v[90:93], v[152:155], v[210:213], v[90:93]
	v_mfma_f32_16x16x32_bf16 v[78:81], v[140:143], v[218:221], v[78:81]
	v_mfma_f32_16x16x32_bf16 v[74:77], v[152:155], v[218:221], v[74:77]
	v_mfma_f32_16x16x32_bf16 v[126:129], v[148:151], v[184:187], v[126:129]
	v_mfma_f32_16x16x32_bf16 v[122:125], v[156:159], v[184:187], v[122:125]
	v_mfma_f32_16x16x32_bf16 v[110:113], v[148:151], v[196:199], v[110:113]
	v_mfma_f32_16x16x32_bf16 v[106:109], v[156:159], v[196:199], v[106:109]
	v_mfma_f32_16x16x32_bf16 v[94:97], v[148:151], v[214:217], v[94:97]
	v_mfma_f32_16x16x32_bf16 v[90:93], v[156:159], v[214:217], v[90:93]
	v_mfma_f32_16x16x32_bf16 v[78:81], v[148:151], v[222:225], v[78:81]
	v_mfma_f32_16x16x32_bf16 v[74:77], v[156:159], v[222:225], v[74:77]
	v_mfma_f32_16x16x32_bf16 v[118:121], v[160:163], v[176:179], v[118:121]
	v_mfma_f32_16x16x32_bf16 v[114:117], v[168:171], v[176:179], v[114:117]
	v_mfma_f32_16x16x32_bf16 v[102:105], v[160:163], v[188:191], v[102:105]
	v_mfma_f32_16x16x32_bf16 v[98:101], v[168:171], v[188:191], v[98:101]
	v_mfma_f32_16x16x32_bf16 v[86:89], v[160:163], v[210:213], v[86:89]
	v_mfma_f32_16x16x32_bf16 v[82:85], v[168:171], v[210:213], v[82:85]
	v_mfma_f32_16x16x32_bf16 v[70:73], v[160:163], v[218:221], v[70:73]
	v_mfma_f32_16x16x32_bf16 v[66:69], v[168:171], v[218:221], v[66:69]
	v_mfma_f32_16x16x32_bf16 v[118:121], v[164:167], v[184:187], v[118:121]
	v_mfma_f32_16x16x32_bf16 v[114:117], v[172:175], v[184:187], v[114:117]
	v_mfma_f32_16x16x32_bf16 v[102:105], v[164:167], v[196:199], v[102:105]
	v_mfma_f32_16x16x32_bf16 v[98:101], v[172:175], v[196:199], v[98:101]
	v_mfma_f32_16x16x32_bf16 v[86:89], v[164:167], v[214:217], v[86:89]
	v_mfma_f32_16x16x32_bf16 v[82:85], v[172:175], v[214:217], v[82:85]
	v_mfma_f32_16x16x32_bf16 v[70:73], v[164:167], v[222:225], v[70:73]
	v_mfma_f32_16x16x32_bf16 v[66:69], v[172:175], v[222:225], v[66:69]
	s_barrier
	s_add_i32 s45, s45, s50
	v_lshl_add_u64 v[180:181], s[30:31], 0, v[0:1]
	s_mov_b32 m0, s45
	ds_read_b128 v[176:179], v147 offset:16384
	ds_read_b128 v[184:187], v147 offset:17408
	ds_read_b128 v[188:191], v147 offset:18432
	ds_read_b128 v[196:199], v147 offset:19456
	ds_read_b128 v[210:213], v147 offset:20480
	ds_read_b128 v[214:217], v147 offset:21504
	ds_read_b128 v[218:221], v147 offset:22528
	ds_read_b128 v[222:225], v147 offset:23552
	global_load_lds_dwordx4 v[180:181], off
	s_add_i32 m0, s45, 0x2000
	s_add_u32 s60, s30, 0x100000
	v_lshl_add_u64 v[192:193], s[30:31], 0, v[130:131]
	s_addc_u32 s61, s31, 0
	s_add_i32 s45, s59, s50
	global_load_lds_dwordx4 v[192:193], off
	v_lshl_add_u64 v[202:203], s[60:61], 0, v[0:1]
	s_mov_b32 m0, s45
	v_lshl_add_u64 v[226:227], s[36:37], 0, v[132:133]
	global_load_lds_dwordx4 v[202:203], off
	v_lshl_add_u64 v[202:203], s[60:61], 0, v[130:131]
	s_add_i32 m0, s45, 0x2000
	s_nop 0
	global_load_lds_dwordx4 v[202:203], off
	v_lshl_add_u64 v[202:203], s[36:37], 0, v[134:135]
	s_mov_b32 m0, s51
	s_nop 0
	global_load_lds_dwordx4 v[202:203], off
	s_mov_b32 m0, s52
	s_nop 0
	global_load_lds_dwordx4 v[226:227], off
	s_waitcnt vmcnt(8)
	s_waitcnt lgkmcnt(0)
	s_barrier
	s_waitcnt lgkmcnt(0)
	v_mfma_f32_16x16x32_bf16 v[62:65], v[140:143], v[176:179], v[62:65]
	v_mfma_f32_16x16x32_bf16 v[58:61], v[152:155], v[176:179], v[58:61]
	v_mfma_f32_16x16x32_bf16 v[46:49], v[140:143], v[188:191], v[46:49]
	v_mfma_f32_16x16x32_bf16 v[42:45], v[152:155], v[188:191], v[42:45]
	v_mfma_f32_16x16x32_bf16 v[30:33], v[140:143], v[210:213], v[30:33]
	v_mfma_f32_16x16x32_bf16 v[26:29], v[152:155], v[210:213], v[26:29]
	v_mfma_f32_16x16x32_bf16 v[14:17], v[140:143], v[218:221], v[14:17]
	v_mfma_f32_16x16x32_bf16 v[10:13], v[152:155], v[218:221], v[10:13]
	v_mfma_f32_16x16x32_bf16 v[62:65], v[148:151], v[184:187], v[62:65]
	v_mfma_f32_16x16x32_bf16 v[58:61], v[156:159], v[184:187], v[58:61]
	v_mfma_f32_16x16x32_bf16 v[46:49], v[148:151], v[196:199], v[46:49]
	v_mfma_f32_16x16x32_bf16 v[42:45], v[156:159], v[196:199], v[42:45]
	v_mfma_f32_16x16x32_bf16 v[30:33], v[148:151], v[214:217], v[30:33]
	v_mfma_f32_16x16x32_bf16 v[26:29], v[156:159], v[214:217], v[26:29]
	v_mfma_f32_16x16x32_bf16 v[14:17], v[148:151], v[222:225], v[14:17]
	v_mfma_f32_16x16x32_bf16 v[10:13], v[156:159], v[222:225], v[10:13]
	v_mfma_f32_16x16x32_bf16 v[54:57], v[160:163], v[176:179], v[54:57]
	v_mfma_f32_16x16x32_bf16 v[50:53], v[168:171], v[176:179], v[50:53]
	v_mfma_f32_16x16x32_bf16 v[38:41], v[160:163], v[188:191], v[38:41]
	v_mfma_f32_16x16x32_bf16 v[34:37], v[168:171], v[188:191], v[34:37]
	v_mfma_f32_16x16x32_bf16 v[22:25], v[160:163], v[210:213], v[22:25]
	v_mfma_f32_16x16x32_bf16 v[18:21], v[168:171], v[210:213], v[18:21]
	v_mfma_f32_16x16x32_bf16 v[6:9], v[160:163], v[218:221], v[6:9]
	v_mfma_f32_16x16x32_bf16 v[2:5], v[168:171], v[218:221], v[2:5]
	v_mfma_f32_16x16x32_bf16 v[54:57], v[164:167], v[184:187], v[54:57]
	v_mfma_f32_16x16x32_bf16 v[50:53], v[172:175], v[184:187], v[50:53]
	v_mfma_f32_16x16x32_bf16 v[38:41], v[164:167], v[196:199], v[38:41]
	v_mfma_f32_16x16x32_bf16 v[34:37], v[172:175], v[196:199], v[34:37]
	v_mfma_f32_16x16x32_bf16 v[22:25], v[164:167], v[214:217], v[22:25]
	v_mfma_f32_16x16x32_bf16 v[18:21], v[172:175], v[214:217], v[18:21]
	v_mfma_f32_16x16x32_bf16 v[6:9], v[164:167], v[222:225], v[6:9]
	v_mfma_f32_16x16x32_bf16 v[2:5], v[172:175], v[222:225], v[2:5]
	s_barrier
	s_add_i32 s45, 0, 0x18000
	s_add_i32 s59, 0, 0x1c000
	v_add_u32_e32 v156, s45, v145
	v_add_u32_e32 v172, s59, v145
	ds_read_b128 v[140:143], v156
	ds_read_b128 v[148:151], v156 offset:1024
	ds_read_b128 v[152:155], v156 offset:2048
	ds_read_b128 v[156:159], v156 offset:3072
	ds_read_b128 v[160:163], v172
	ds_read_b128 v[164:167], v172 offset:1024
	ds_read_b128 v[168:171], v172 offset:2048
	ds_read_b128 v[172:175], v172 offset:3072
	s_add_u32 s36, s36, 0x100000
	s_addc_u32 s37, s37, 0
	s_mov_b32 m0, s53
	v_lshl_add_u64 v[228:229], s[36:37], 0, v[134:135]
	ds_read_b128 v[176:179], v147 offset:32768
	ds_read_b128 v[184:187], v147 offset:33792
	ds_read_b128 v[188:191], v147 offset:34816
	ds_read_b128 v[196:199], v147 offset:35840
	ds_read_b128 v[210:213], v147 offset:36864
	ds_read_b128 v[214:217], v147 offset:37888
	ds_read_b128 v[218:221], v147 offset:38912
	ds_read_b128 v[222:225], v147 offset:39936
	global_load_lds_dwordx4 v[228:229], off
	v_lshl_add_u64 v[228:229], s[36:37], 0, v[132:133]
	s_mov_b32 m0, s54
	s_nop 0
	global_load_lds_dwordx4 v[228:229], off
	s_waitcnt vmcnt(8)
	s_waitcnt lgkmcnt(0)
	s_barrier
	s_waitcnt lgkmcnt(0)
	v_mfma_f32_16x16x32_bf16 v[126:129], v[140:143], v[176:179], v[126:129]
	v_mfma_f32_16x16x32_bf16 v[122:125], v[152:155], v[176:179], v[122:125]
	v_mfma_f32_16x16x32_bf16 v[110:113], v[140:143], v[188:191], v[110:113]
	v_mfma_f32_16x16x32_bf16 v[106:109], v[152:155], v[188:191], v[106:109]
	v_mfma_f32_16x16x32_bf16 v[94:97], v[140:143], v[210:213], v[94:97]
	v_mfma_f32_16x16x32_bf16 v[90:93], v[152:155], v[210:213], v[90:93]
	v_mfma_f32_16x16x32_bf16 v[78:81], v[140:143], v[218:221], v[78:81]
	v_mfma_f32_16x16x32_bf16 v[74:77], v[152:155], v[218:221], v[74:77]
	v_mfma_f32_16x16x32_bf16 v[126:129], v[148:151], v[184:187], v[126:129]
	v_mfma_f32_16x16x32_bf16 v[122:125], v[156:159], v[184:187], v[122:125]
	v_mfma_f32_16x16x32_bf16 v[110:113], v[148:151], v[196:199], v[110:113]
	v_mfma_f32_16x16x32_bf16 v[106:109], v[156:159], v[196:199], v[106:109]
	v_mfma_f32_16x16x32_bf16 v[94:97], v[148:151], v[214:217], v[94:97]
	v_mfma_f32_16x16x32_bf16 v[90:93], v[156:159], v[214:217], v[90:93]
	v_mfma_f32_16x16x32_bf16 v[78:81], v[148:151], v[222:225], v[78:81]
	v_mfma_f32_16x16x32_bf16 v[74:77], v[156:159], v[222:225], v[74:77]
	v_mfma_f32_16x16x32_bf16 v[118:121], v[160:163], v[176:179], v[118:121]
	v_mfma_f32_16x16x32_bf16 v[114:117], v[168:171], v[176:179], v[114:117]
	v_mfma_f32_16x16x32_bf16 v[102:105], v[160:163], v[188:191], v[102:105]
	v_mfma_f32_16x16x32_bf16 v[98:101], v[168:171], v[188:191], v[98:101]
	v_mfma_f32_16x16x32_bf16 v[86:89], v[160:163], v[210:213], v[86:89]
	v_mfma_f32_16x16x32_bf16 v[82:85], v[168:171], v[210:213], v[82:85]
	v_mfma_f32_16x16x32_bf16 v[70:73], v[160:163], v[218:221], v[70:73]
	v_mfma_f32_16x16x32_bf16 v[66:69], v[168:171], v[218:221], v[66:69]
	v_mfma_f32_16x16x32_bf16 v[118:121], v[164:167], v[184:187], v[118:121]
	v_mfma_f32_16x16x32_bf16 v[114:117], v[172:175], v[184:187], v[114:117]
	v_mfma_f32_16x16x32_bf16 v[102:105], v[164:167], v[196:199], v[102:105]
	v_mfma_f32_16x16x32_bf16 v[98:101], v[172:175], v[196:199], v[98:101]
	v_mfma_f32_16x16x32_bf16 v[86:89], v[164:167], v[214:217], v[86:89]
	v_mfma_f32_16x16x32_bf16 v[82:85], v[172:175], v[214:217], v[82:85]
	v_mfma_f32_16x16x32_bf16 v[70:73], v[164:167], v[222:225], v[70:73]
	v_mfma_f32_16x16x32_bf16 v[66:69], v[172:175], v[222:225], v[66:69]
	s_barrier
	s_add_i32 s36, s45, s50
	v_lshl_add_u64 v[180:181], v[180:181], 0, s[22:23]
	s_mov_b32 m0, s36
	ds_read_b128 v[176:179], v147 offset:49152
	ds_read_b128 v[184:187], v147 offset:50176
	ds_read_b128 v[188:191], v147 offset:51200
	ds_read_b128 v[196:199], v147 offset:52224
	ds_read_b128 v[210:213], v147 offset:53248
	ds_read_b128 v[214:217], v147 offset:54272
	ds_read_b128 v[218:221], v147 offset:55296
	ds_read_b128 v[222:225], v147 offset:56320
	global_load_lds_dwordx4 v[180:181], off
	s_add_i32 m0, s36, 0x2000
	s_add_u32 s30, s30, 0x100080
	v_lshl_add_u64 v[180:181], v[192:193], 0, s[22:23]
	s_addc_u32 s31, s31, 0
	s_add_i32 s36, s59, s50
	global_load_lds_dwordx4 v[180:181], off
	v_lshl_add_u64 v[180:181], s[30:31], 0, v[0:1]
	s_mov_b32 m0, s36
	s_nop 0
	global_load_lds_dwordx4 v[180:181], off
	v_lshl_add_u64 v[180:181], s[30:31], 0, v[130:131]
	s_add_i32 m0, s36, 0x2000
	s_nop 0
	global_load_lds_dwordx4 v[180:181], off
	v_lshl_add_u64 v[180:181], v[202:203], 0, s[22:23]
	s_mov_b32 m0, s56
	s_nop 0
	global_load_lds_dwordx4 v[180:181], off
	v_lshl_add_u64 v[180:181], v[226:227], 0, s[22:23]
	s_mov_b32 m0, s57
	s_nop 0
	global_load_lds_dwordx4 v[180:181], off
	s_waitcnt vmcnt(8)
	s_waitcnt lgkmcnt(0)
	s_barrier
	s_waitcnt lgkmcnt(0)
	v_mfma_f32_16x16x32_bf16 v[62:65], v[140:143], v[176:179], v[62:65]
	v_mfma_f32_16x16x32_bf16 v[58:61], v[152:155], v[176:179], v[58:61]
	v_mfma_f32_16x16x32_bf16 v[46:49], v[140:143], v[188:191], v[46:49]
	v_mfma_f32_16x16x32_bf16 v[42:45], v[152:155], v[188:191], v[42:45]
	v_mfma_f32_16x16x32_bf16 v[30:33], v[140:143], v[210:213], v[30:33]
	v_mfma_f32_16x16x32_bf16 v[26:29], v[152:155], v[210:213], v[26:29]
	v_mfma_f32_16x16x32_bf16 v[14:17], v[140:143], v[218:221], v[14:17]
	v_mfma_f32_16x16x32_bf16 v[10:13], v[152:155], v[218:221], v[10:13]
	v_mfma_f32_16x16x32_bf16 v[62:65], v[148:151], v[184:187], v[62:65]
	v_mfma_f32_16x16x32_bf16 v[58:61], v[156:159], v[184:187], v[58:61]
	v_mfma_f32_16x16x32_bf16 v[46:49], v[148:151], v[196:199], v[46:49]
	v_mfma_f32_16x16x32_bf16 v[42:45], v[156:159], v[196:199], v[42:45]
	v_mfma_f32_16x16x32_bf16 v[30:33], v[148:151], v[214:217], v[30:33]
	v_mfma_f32_16x16x32_bf16 v[26:29], v[156:159], v[214:217], v[26:29]
	v_mfma_f32_16x16x32_bf16 v[14:17], v[148:151], v[222:225], v[14:17]
	v_mfma_f32_16x16x32_bf16 v[10:13], v[156:159], v[222:225], v[10:13]
	v_mfma_f32_16x16x32_bf16 v[54:57], v[160:163], v[176:179], v[54:57]
	v_mfma_f32_16x16x32_bf16 v[50:53], v[168:171], v[176:179], v[50:53]
	v_mfma_f32_16x16x32_bf16 v[38:41], v[160:163], v[188:191], v[38:41]
	v_mfma_f32_16x16x32_bf16 v[34:37], v[168:171], v[188:191], v[34:37]
	v_mfma_f32_16x16x32_bf16 v[22:25], v[160:163], v[210:213], v[22:25]
	v_mfma_f32_16x16x32_bf16 v[18:21], v[168:171], v[210:213], v[18:21]
	v_mfma_f32_16x16x32_bf16 v[6:9], v[160:163], v[218:221], v[6:9]
	v_mfma_f32_16x16x32_bf16 v[2:5], v[168:171], v[218:221], v[2:5]
	v_mfma_f32_16x16x32_bf16 v[54:57], v[164:167], v[184:187], v[54:57]
	v_mfma_f32_16x16x32_bf16 v[50:53], v[172:175], v[184:187], v[50:53]
	v_mfma_f32_16x16x32_bf16 v[38:41], v[164:167], v[196:199], v[38:41]
	v_mfma_f32_16x16x32_bf16 v[34:37], v[172:175], v[196:199], v[34:37]
	v_mfma_f32_16x16x32_bf16 v[22:25], v[164:167], v[214:217], v[22:25]
	v_mfma_f32_16x16x32_bf16 v[18:21], v[172:175], v[214:217], v[18:21]
	v_mfma_f32_16x16x32_bf16 v[6:9], v[164:167], v[222:225], v[6:9]
	v_mfma_f32_16x16x32_bf16 v[2:5], v[172:175], v[222:225], v[2:5]
	s_barrier
	s_add_i32 s35, s35, 2
	s_add_u32 s12, s12, 0x100
	s_addc_u32 s13, s13, 0
	s_add_u32 s26, s26, 0x100
	s_addc_u32 s28, s28, 0
	s_cmp_gt_u32 s35, 61
	s_cbranch_scc0 .LBB0_864
	s_and_b64 vcc, exec, s[20:21]
	s_cbranch_vccz .LBB0_867
	s_barrier

.LBB0_919:
	s_andn2_saveexec_b64 s[2:3], s[6:7]
	s_cbranch_execz .LBB0_939
	s_mov_b64 s[6:7], exec
	s_setprio 0
	buffer_wbl2 sc1
	s_waitcnt lgkmcnt(0)
	s_waitcnt vmcnt(0)
	v_mbcnt_lo_u32_b32 v0, s6, 0
	v_mbcnt_hi_u32_b32 v0, s7, v0
	v_cmp_eq_u32_e32 vcc, 0, v0
	s_and_saveexec_b64 s[10:11], vcc
	s_cbranch_execz .LBB0_922
	s_bcnt1_i32_b64 s0, s[6:7]
	v_readlane_b32 s2, v253, 61
	v_mov_b32_e32 v3, s0
	v_readlane_b32 s3, v253, 62
	s_nop 4
	global_atomic_add v3, v1, v3, s[2:3] sc0

.Lsprio_4:
.LBB0_957:
	s_add_i32 s52, s40, 2
	s_add_u32 s53, s36, 0x80
	s_addc_u32 s41, s37, 0
	s_add_i32 s56, 0, 0x10000
	s_cmp_eq_u32 s44, s40
	s_cselect_b32 s41, s7, s41
	s_cselect_b32 s40, s6, s53
	s_cselect_b32 s55, s35, s51
	s_cselect_b32 s54, s34, s50
	s_add_i32 s53, 0, 0x14000
	v_add_u32_e32 v154, s56, v140
	v_add_u32_e32 v170, s53, v140
	ds_read_b128 v[142:145], v154
	ds_read_b128 v[146:149], v154 offset:1024
	ds_read_b128 v[150:153], v154 offset:2048
	ds_read_b128 v[154:157], v154 offset:3072
	ds_read_b128 v[158:161], v170
	ds_read_b128 v[162:165], v170 offset:1024
	ds_read_b128 v[166:169], v170 offset:2048
	ds_read_b128 v[170:173], v170 offset:3072
	v_lshl_add_u64 v[192:193], s[36:37], 0, v[136:137]
	s_add_i32 m0, s18, 0xc000
	ds_read_b128 v[174:177], v141
	ds_read_b128 v[178:181], v141 offset:1024
	ds_read_b128 v[184:187], v141 offset:2048
	ds_read_b128 v[188:191], v141 offset:3072
	ds_read_b128 v[196:199], v141 offset:4096
	ds_read_b128 v[210:213], v141 offset:5120
	ds_read_b128 v[214:217], v141 offset:6144
	ds_read_b128 v[218:221], v141 offset:7168
	global_load_lds_dwordx4 v[192:193], off
	v_lshl_add_u64 v[192:193], s[36:37], 0, v[138:139]
	s_add_i32 m0, s18, 0xe000
	s_nop 0
	global_load_lds_dwordx4 v[192:193], off
	s_waitcnt vmcnt(8)
	s_waitcnt lgkmcnt(0)
	s_barrier
	s_waitcnt lgkmcnt(0)
	v_mfma_f32_16x16x32_bf16 v[122:125], v[142:145], v[174:177], v[122:125]
	v_mfma_f32_16x16x32_bf16 v[126:129], v[150:153], v[174:177], v[126:129]
	v_mfma_f32_16x16x32_bf16 v[110:113], v[142:145], v[184:187], v[110:113]
	v_mfma_f32_16x16x32_bf16 v[106:109], v[150:153], v[184:187], v[106:109]
	v_mfma_f32_16x16x32_bf16 v[94:97], v[142:145], v[196:199], v[94:97]
	v_mfma_f32_16x16x32_bf16 v[90:93], v[150:153], v[196:199], v[90:93]
	v_mfma_f32_16x16x32_bf16 v[78:81], v[142:145], v[214:217], v[78:81]
	v_mfma_f32_16x16x32_bf16 v[74:77], v[150:153], v[214:217], v[74:77]
	v_mfma_f32_16x16x32_bf16 v[122:125], v[146:149], v[178:181], v[122:125]
	v_mfma_f32_16x16x32_bf16 v[126:129], v[154:157], v[178:181], v[126:129]
	v_mfma_f32_16x16x32_bf16 v[110:113], v[146:149], v[188:191], v[110:113]
	v_mfma_f32_16x16x32_bf16 v[106:109], v[154:157], v[188:191], v[106:109]
	v_mfma_f32_16x16x32_bf16 v[94:97], v[146:149], v[210:213], v[94:97]
	v_mfma_f32_16x16x32_bf16 v[90:93], v[154:157], v[210:213], v[90:93]
	v_mfma_f32_16x16x32_bf16 v[78:81], v[146:149], v[218:221], v[78:81]
	v_mfma_f32_16x16x32_bf16 v[74:77], v[154:157], v[218:221], v[74:77]
	v_mfma_f32_16x16x32_bf16 v[118:121], v[158:161], v[174:177], v[118:121]
	v_mfma_f32_16x16x32_bf16 v[114:117], v[166:169], v[174:177], v[114:117]
	v_mfma_f32_16x16x32_bf16 v[102:105], v[158:161], v[184:187], v[102:105]
	v_mfma_f32_16x16x32_bf16 v[98:101], v[166:169], v[184:187], v[98:101]
	v_mfma_f32_16x16x32_bf16 v[86:89], v[158:161], v[196:199], v[86:89]
	v_mfma_f32_16x16x32_bf16 v[82:85], v[166:169], v[196:199], v[82:85]
	v_mfma_f32_16x16x32_bf16 v[70:73], v[158:161], v[214:217], v[70:73]
	v_mfma_f32_16x16x32_bf16 v[66:69], v[166:169], v[214:217], v[66:69]
	v_mfma_f32_16x16x32_bf16 v[118:121], v[162:165], v[178:181], v[118:121]
	v_mfma_f32_16x16x32_bf16 v[114:117], v[170:173], v[178:181], v[114:117]
	v_mfma_f32_16x16x32_bf16 v[102:105], v[162:165], v[188:191], v[102:105]
	v_mfma_f32_16x16x32_bf16 v[98:101], v[170:173], v[188:191], v[98:101]
	v_mfma_f32_16x16x32_bf16 v[86:89], v[162:165], v[210:213], v[86:89]
	v_mfma_f32_16x16x32_bf16 v[82:85], v[170:173], v[210:213], v[82:85]
	v_mfma_f32_16x16x32_bf16 v[70:73], v[162:165], v[218:221], v[70:73]
	v_mfma_f32_16x16x32_bf16 v[66:69], v[170:173], v[218:221], v[66:69]
	s_barrier
	s_add_i32 s56, s56, s17
	v_lshl_add_u64 v[192:193], s[54:55], 0, v[0:1]
	s_mov_b32 m0, s56
	ds_read_b128 v[174:177], v141 offset:16384
	ds_read_b128 v[178:181], v141 offset:17408
	ds_read_b128 v[184:187], v141 offset:18432
	ds_read_b128 v[188:191], v141 offset:19456
	ds_read_b128 v[196:199], v141 offset:20480
	ds_read_b128 v[210:213], v141 offset:21504
	ds_read_b128 v[214:217], v141 offset:22528
	ds_read_b128 v[218:221], v141 offset:23552
	global_load_lds_dwordx4 v[192:193], off
	s_add_i32 m0, s56, 0x2000
	v_lshl_add_u64 v[202:203], s[54:55], 0, v[130:131]
	s_add_u32 s54, s54, s10
	s_addc_u32 s55, s55, s11
	s_add_i32 s53, s53, s17
	global_load_lds_dwordx4 v[202:203], off
	v_lshl_add_u64 v[222:223], s[54:55], 0, v[0:1]
	s_mov_b32 m0, s53
	v_lshl_add_u64 v[224:225], s[54:55], 0, v[130:131]
	global_load_lds_dwordx4 v[222:223], off
	s_add_i32 m0, s53, 0x2000
	v_lshl_add_u64 v[226:227], s[40:41], 0, v[134:135]
	global_load_lds_dwordx4 v[224:225], off
	s_mov_b32 m0, s18
	v_lshl_add_u64 v[228:229], s[40:41], 0, v[132:133]
	global_load_lds_dwordx4 v[226:227], off
	s_mov_b32 m0, s19
	s_nop 0
	global_load_lds_dwordx4 v[228:229], off
	s_waitcnt vmcnt(8)
	s_waitcnt lgkmcnt(0)
	s_barrier
	s_waitcnt lgkmcnt(0)
	v_mfma_f32_16x16x32_bf16 v[62:65], v[142:145], v[174:177], v[62:65]
	v_mfma_f32_16x16x32_bf16 v[58:61], v[150:153], v[174:177], v[58:61]
	v_mfma_f32_16x16x32_bf16 v[46:49], v[142:145], v[184:187], v[46:49]
	v_mfma_f32_16x16x32_bf16 v[42:45], v[150:153], v[184:187], v[42:45]
	v_mfma_f32_16x16x32_bf16 v[30:33], v[142:145], v[196:199], v[30:33]
	v_mfma_f32_16x16x32_bf16 v[26:29], v[150:153], v[196:199], v[26:29]
	v_mfma_f32_16x16x32_bf16 v[14:17], v[142:145], v[214:217], v[14:17]
	v_mfma_f32_16x16x32_bf16 v[10:13], v[150:153], v[214:217], v[10:13]
	v_mfma_f32_16x16x32_bf16 v[62:65], v[146:149], v[178:181], v[62:65]
	v_mfma_f32_16x16x32_bf16 v[58:61], v[154:157], v[178:181], v[58:61]
	v_mfma_f32_16x16x32_bf16 v[46:49], v[146:149], v[188:191], v[46:49]
	v_mfma_f32_16x16x32_bf16 v[42:45], v[154:157], v[188:191], v[42:45]
	v_mfma_f32_16x16x32_bf16 v[30:33], v[146:149], v[210:213], v[30:33]
	v_mfma_f32_16x16x32_bf16 v[26:29], v[154:157], v[210:213], v[26:29]
	v_mfma_f32_16x16x32_bf16 v[14:17], v[146:149], v[218:221], v[14:17]
	v_mfma_f32_16x16x32_bf16 v[10:13], v[154:157], v[218:221], v[10:13]
	v_mfma_f32_16x16x32_bf16 v[54:57], v[158:161], v[174:177], v[54:57]
	v_mfma_f32_16x16x32_bf16 v[50:53], v[166:169], v[174:177], v[50:53]
	v_mfma_f32_16x16x32_bf16 v[38:41], v[158:161], v[184:187], v[38:41]
	v_mfma_f32_16x16x32_bf16 v[34:37], v[166:169], v[184:187], v[34:37]
	v_mfma_f32_16x16x32_bf16 v[22:25], v[158:161], v[196:199], v[22:25]
	v_mfma_f32_16x16x32_bf16 v[18:21], v[166:169], v[196:199], v[18:21]
	v_mfma_f32_16x16x32_bf16 v[6:9], v[158:161], v[214:217], v[6:9]
	v_mfma_f32_16x16x32_bf16 v[2:5], v[166:169], v[214:217], v[2:5]
	v_mfma_f32_16x16x32_bf16 v[54:57], v[162:165], v[178:181], v[54:57]
	v_mfma_f32_16x16x32_bf16 v[50:53], v[170:173], v[178:181], v[50:53]
	v_mfma_f32_16x16x32_bf16 v[38:41], v[162:165], v[188:191], v[38:41]
	v_mfma_f32_16x16x32_bf16 v[34:37], v[170:173], v[188:191], v[34:37]
	v_mfma_f32_16x16x32_bf16 v[22:25], v[162:165], v[210:213], v[22:25]
	v_mfma_f32_16x16x32_bf16 v[18:21], v[170:173], v[210:213], v[18:21]
	v_mfma_f32_16x16x32_bf16 v[6:9], v[162:165], v[218:221], v[6:9]
	v_mfma_f32_16x16x32_bf16 v[2:5], v[170:173], v[218:221], v[2:5]
	s_barrier
	s_add_i32 s53, 0, 0x18000
	s_add_i32 s54, 0, 0x1c000
	v_add_u32_e32 v154, s53, v140
	v_add_u32_e32 v170, s54, v140
	ds_read_b128 v[142:145], v154
	ds_read_b128 v[146:149], v154 offset:1024
	ds_read_b128 v[150:153], v154 offset:2048
	ds_read_b128 v[154:157], v154 offset:3072
	ds_read_b128 v[158:161], v170
	ds_read_b128 v[162:165], v170 offset:1024
	ds_read_b128 v[166:169], v170 offset:2048
	ds_read_b128 v[170:173], v170 offset:3072
	s_add_u32 s40, s40, s10
	s_addc_u32 s41, s41, s11
	s_mov_b32 m0, s24
	v_lshl_add_u64 v[230:231], s[40:41], 0, v[134:135]
	ds_read_b128 v[174:177], v141 offset:32768
	ds_read_b128 v[178:181], v141 offset:33792
	ds_read_b128 v[184:187], v141 offset:34816
	ds_read_b128 v[188:191], v141 offset:35840
	ds_read_b128 v[196:199], v141 offset:36864
	ds_read_b128 v[210:213], v141 offset:37888
	ds_read_b128 v[214:217], v141 offset:38912
	ds_read_b128 v[218:221], v141 offset:39936
	global_load_lds_dwordx4 v[230:231], off
	v_lshl_add_u64 v[230:231], s[40:41], 0, v[132:133]
	s_mov_b32 m0, s25
	s_nop 0
	global_load_lds_dwordx4 v[230:231], off
	s_waitcnt vmcnt(8)
	s_waitcnt lgkmcnt(0)
	s_barrier
	s_waitcnt lgkmcnt(0)
	v_mfma_f32_16x16x32_bf16 v[122:125], v[142:145], v[174:177], v[122:125]
	v_mfma_f32_16x16x32_bf16 v[126:129], v[150:153], v[174:177], v[126:129]
	v_mfma_f32_16x16x32_bf16 v[110:113], v[142:145], v[184:187], v[110:113]
	v_mfma_f32_16x16x32_bf16 v[106:109], v[150:153], v[184:187], v[106:109]
	v_mfma_f32_16x16x32_bf16 v[94:97], v[142:145], v[196:199], v[94:97]
	v_mfma_f32_16x16x32_bf16 v[90:93], v[150:153], v[196:199], v[90:93]
	v_mfma_f32_16x16x32_bf16 v[78:81], v[142:145], v[214:217], v[78:81]
	v_mfma_f32_16x16x32_bf16 v[74:77], v[150:153], v[214:217], v[74:77]
	v_mfma_f32_16x16x32_bf16 v[122:125], v[146:149], v[178:181], v[122:125]
	v_mfma_f32_16x16x32_bf16 v[126:129], v[154:157], v[178:181], v[126:129]
	v_mfma_f32_16x16x32_bf16 v[110:113], v[146:149], v[188:191], v[110:113]
	v_mfma_f32_16x16x32_bf16 v[106:109], v[154:157], v[188:191], v[106:109]
	v_mfma_f32_16x16x32_bf16 v[94:97], v[146:149], v[210:213], v[94:97]
	v_mfma_f32_16x16x32_bf16 v[90:93], v[154:157], v[210:213], v[90:93]
	v_mfma_f32_16x16x32_bf16 v[78:81], v[146:149], v[218:221], v[78:81]
	v_mfma_f32_16x16x32_bf16 v[74:77], v[154:157], v[218:221], v[74:77]
	v_mfma_f32_16x16x32_bf16 v[118:121], v[158:161], v[174:177], v[118:121]
	v_mfma_f32_16x16x32_bf16 v[114:117], v[166:169], v[174:177], v[114:117]
	v_mfma_f32_16x16x32_bf16 v[102:105], v[158:161], v[184:187], v[102:105]
	v_mfma_f32_16x16x32_bf16 v[98:101], v[166:169], v[184:187], v[98:101]
	v_mfma_f32_16x16x32_bf16 v[86:89], v[158:161], v[196:199], v[86:89]
	v_mfma_f32_16x16x32_bf16 v[82:85], v[166:169], v[196:199], v[82:85]
	v_mfma_f32_16x16x32_bf16 v[70:73], v[158:161], v[214:217], v[70:73]
	v_mfma_f32_16x16x32_bf16 v[66:69], v[166:169], v[214:217], v[66:69]
	v_mfma_f32_16x16x32_bf16 v[118:121], v[162:165], v[178:181], v[118:121]
	v_mfma_f32_16x16x32_bf16 v[114:117], v[170:173], v[178:181], v[114:117]
	v_mfma_f32_16x16x32_bf16 v[102:105], v[162:165], v[188:191], v[102:105]
	v_mfma_f32_16x16x32_bf16 v[98:101], v[170:173], v[188:191], v[98:101]
	v_mfma_f32_16x16x32_bf16 v[86:89], v[162:165], v[210:213], v[86:89]
	v_mfma_f32_16x16x32_bf16 v[82:85], v[170:173], v[210:213], v[82:85]
	v_mfma_f32_16x16x32_bf16 v[70:73], v[162:165], v[218:221], v[70:73]
	v_mfma_f32_16x16x32_bf16 v[66:69], v[170:173], v[218:221], v[66:69]
	s_barrier
	s_add_i32 s40, s53, s17
	v_lshl_add_u64 v[192:193], v[192:193], 0, s[22:23]
	s_mov_b32 m0, s40
	ds_read_b128 v[174:177], v141 offset:49152
	ds_read_b128 v[178:181], v141 offset:50176
	ds_read_b128 v[184:187], v141 offset:51200
	ds_read_b128 v[188:191], v141 offset:52224
	ds_read_b128 v[196:199], v141 offset:53248
	ds_read_b128 v[210:213], v141 offset:54272
	ds_read_b128 v[214:217], v141 offset:55296
	ds_read_b128 v[218:221], v141 offset:56320
	global_load_lds_dwordx4 v[192:193], off
	v_lshl_add_u64 v[192:193], v[202:203], 0, s[22:23]
	s_add_i32 m0, s40, 0x2000
	s_add_i32 s40, s54, s17
	global_load_lds_dwordx4 v[192:193], off
	v_lshl_add_u64 v[192:193], v[222:223], 0, s[22:23]
	s_mov_b32 m0, s40
	s_nop 0
	global_load_lds_dwordx4 v[192:193], off
	v_lshl_add_u64 v[192:193], v[224:225], 0, s[22:23]
	s_add_i32 m0, s40, 0x2000
	s_nop 0
	global_load_lds_dwordx4 v[192:193], off
	v_lshl_add_u64 v[192:193], v[226:227], 0, s[22:23]
	s_mov_b32 m0, s42
	s_nop 0
	global_load_lds_dwordx4 v[192:193], off
	v_lshl_add_u64 v[192:193], v[228:229], 0, s[22:23]
	s_mov_b32 m0, s43
	s_nop 0
	global_load_lds_dwordx4 v[192:193], off
	s_waitcnt vmcnt(8)
	s_waitcnt lgkmcnt(0)
	s_barrier
	s_waitcnt lgkmcnt(0)
	v_mfma_f32_16x16x32_bf16 v[62:65], v[142:145], v[174:177], v[62:65]
	v_mfma_f32_16x16x32_bf16 v[58:61], v[150:153], v[174:177], v[58:61]
	v_mfma_f32_16x16x32_bf16 v[46:49], v[142:145], v[184:187], v[46:49]
	v_mfma_f32_16x16x32_bf16 v[42:45], v[150:153], v[184:187], v[42:45]
	v_mfma_f32_16x16x32_bf16 v[30:33], v[142:145], v[196:199], v[30:33]
	v_mfma_f32_16x16x32_bf16 v[26:29], v[150:153], v[196:199], v[26:29]
	v_mfma_f32_16x16x32_bf16 v[14:17], v[142:145], v[214:217], v[14:17]
	v_mfma_f32_16x16x32_bf16 v[10:13], v[150:153], v[214:217], v[10:13]
	v_mfma_f32_16x16x32_bf16 v[62:65], v[146:149], v[178:181], v[62:65]
	v_mfma_f32_16x16x32_bf16 v[58:61], v[154:157], v[178:181], v[58:61]
	v_mfma_f32_16x16x32_bf16 v[46:49], v[146:149], v[188:191], v[46:49]
	v_mfma_f32_16x16x32_bf16 v[42:45], v[154:157], v[188:191], v[42:45]
	v_mfma_f32_16x16x32_bf16 v[30:33], v[146:149], v[210:213], v[30:33]
	v_mfma_f32_16x16x32_bf16 v[26:29], v[154:157], v[210:213], v[26:29]
	v_mfma_f32_16x16x32_bf16 v[14:17], v[146:149], v[218:221], v[14:17]
	v_mfma_f32_16x16x32_bf16 v[10:13], v[154:157], v[218:221], v[10:13]
	v_mfma_f32_16x16x32_bf16 v[54:57], v[158:161], v[174:177], v[54:57]
	v_mfma_f32_16x16x32_bf16 v[50:53], v[166:169], v[174:177], v[50:53]
	v_mfma_f32_16x16x32_bf16 v[38:41], v[158:161], v[184:187], v[38:41]
	v_mfma_f32_16x16x32_bf16 v[34:37], v[166:169], v[184:187], v[34:37]
	v_mfma_f32_16x16x32_bf16 v[22:25], v[158:161], v[196:199], v[22:25]
	v_mfma_f32_16x16x32_bf16 v[18:21], v[166:169], v[196:199], v[18:21]
	v_mfma_f32_16x16x32_bf16 v[6:9], v[158:161], v[214:217], v[6:9]
	v_mfma_f32_16x16x32_bf16 v[2:5], v[166:169], v[214:217], v[2:5]
	v_mfma_f32_16x16x32_bf16 v[54:57], v[162:165], v[178:181], v[54:57]
	v_mfma_f32_16x16x32_bf16 v[50:53], v[170:173], v[178:181], v[50:53]
	v_mfma_f32_16x16x32_bf16 v[38:41], v[162:165], v[188:191], v[38:41]
	v_mfma_f32_16x16x32_bf16 v[34:37], v[170:173], v[188:191], v[34:37]
	v_mfma_f32_16x16x32_bf16 v[22:25], v[162:165], v[210:213], v[22:25]
	v_mfma_f32_16x16x32_bf16 v[18:21], v[170:173], v[210:213], v[18:21]
	v_mfma_f32_16x16x32_bf16 v[6:9], v[162:165], v[218:221], v[6:9]
	v_mfma_f32_16x16x32_bf16 v[2:5], v[170:173], v[218:221], v[2:5]
	s_barrier
	s_add_u32 s36, s36, 0x100
	s_addc_u32 s37, s37, 0
	s_add_u32 s50, s50, 0x100
	s_addc_u32 s51, s51, 0
	s_cmp_ge_i32 s52, s29
	s_mov_b32 s40, s52
	s_cbranch_scc0 .LBB0_957

.Lsprio_5:
.LBB0_986:
	s_add_u32 s25, s12, 0xfffc0080
	s_addc_u32 s26, s13, -1
	s_add_i32 s28, 0, 0x10000
	s_cmp_eq_u32 s24, 12
	s_cselect_b32 s37, s3, s26
	s_cselect_b32 s36, s16, s25
	v_add_u32_e32 v144, s28, v147
	s_cselect_b32 s31, s15, s21
	s_cselect_b32 s30, s18, s19
	s_add_i32 s25, 0, 0x14000
	ds_read_b128 v[140:143], v144
	ds_read_b128 v[152:155], v144 offset:1024
	ds_read_b128 v[156:159], v144 offset:2048
	ds_read_b128 v[160:163], v144 offset:3072
	v_add_u32_e32 v144, s25, v147
	ds_read_b128 v[164:167], v144
	ds_read_b128 v[168:171], v144 offset:1024
	ds_read_b128 v[172:175], v144 offset:2048
	ds_read_b128 v[176:179], v144 offset:3072
	v_lshl_add_u64 v[144:145], s[12:13], 0, v[136:137]
	s_add_i32 m0, s47, 0xc000
	ds_read_b128 v[184:187], v150
	ds_read_b128 v[188:191], v150 offset:1024
	ds_read_b128 v[196:199], v150 offset:2048
	ds_read_b128 v[210:213], v150 offset:3072
	ds_read_b128 v[214:217], v150 offset:4096
	ds_read_b128 v[218:221], v150 offset:5120
	ds_read_b128 v[222:225], v150 offset:6144
	ds_read_b128 v[226:229], v150 offset:7168
	global_load_lds_dwordx4 v[144:145], off
	v_lshl_add_u64 v[144:145], s[12:13], 0, v[138:139]
	s_add_i32 m0, s47, 0xe000
	s_nop 0
	global_load_lds_dwordx4 v[144:145], off
	s_waitcnt vmcnt(8)
	s_waitcnt lgkmcnt(0)
	s_barrier
	s_waitcnt lgkmcnt(0)
	v_mfma_f32_16x16x32_bf16 v[126:129], v[140:143], v[184:187], v[126:129]
	v_mfma_f32_16x16x32_bf16 v[122:125], v[156:159], v[184:187], v[122:125]
	v_mfma_f32_16x16x32_bf16 v[110:113], v[140:143], v[196:199], v[110:113]
	v_mfma_f32_16x16x32_bf16 v[106:109], v[156:159], v[196:199], v[106:109]
	v_mfma_f32_16x16x32_bf16 v[94:97], v[140:143], v[214:217], v[94:97]
	v_mfma_f32_16x16x32_bf16 v[90:93], v[156:159], v[214:217], v[90:93]
	v_mfma_f32_16x16x32_bf16 v[78:81], v[140:143], v[222:225], v[78:81]
	v_mfma_f32_16x16x32_bf16 v[74:77], v[156:159], v[222:225], v[74:77]
	v_mfma_f32_16x16x32_bf16 v[126:129], v[152:155], v[188:191], v[126:129]
	v_mfma_f32_16x16x32_bf16 v[122:125], v[160:163], v[188:191], v[122:125]
	v_mfma_f32_16x16x32_bf16 v[110:113], v[152:155], v[210:213], v[110:113]
	v_mfma_f32_16x16x32_bf16 v[106:109], v[160:163], v[210:213], v[106:109]
	v_mfma_f32_16x16x32_bf16 v[94:97], v[152:155], v[218:221], v[94:97]
	v_mfma_f32_16x16x32_bf16 v[90:93], v[160:163], v[218:221], v[90:93]
	v_mfma_f32_16x16x32_bf16 v[78:81], v[152:155], v[226:229], v[78:81]
	v_mfma_f32_16x16x32_bf16 v[74:77], v[160:163], v[226:229], v[74:77]
	v_mfma_f32_16x16x32_bf16 v[118:121], v[164:167], v[184:187], v[118:121]
	v_mfma_f32_16x16x32_bf16 v[114:117], v[172:175], v[184:187], v[114:117]
	v_mfma_f32_16x16x32_bf16 v[102:105], v[164:167], v[196:199], v[102:105]
	v_mfma_f32_16x16x32_bf16 v[98:101], v[172:175], v[196:199], v[98:101]
	v_mfma_f32_16x16x32_bf16 v[86:89], v[164:167], v[214:217], v[86:89]
	v_mfma_f32_16x16x32_bf16 v[82:85], v[172:175], v[214:217], v[82:85]
	v_mfma_f32_16x16x32_bf16 v[70:73], v[164:167], v[222:225], v[70:73]
	v_mfma_f32_16x16x32_bf16 v[66:69], v[172:175], v[222:225], v[66:69]
	v_mfma_f32_16x16x32_bf16 v[118:121], v[168:171], v[188:191], v[118:121]
	v_mfma_f32_16x16x32_bf16 v[114:117], v[176:179], v[188:191], v[114:117]
	v_mfma_f32_16x16x32_bf16 v[102:105], v[168:171], v[210:213], v[102:105]
	v_mfma_f32_16x16x32_bf16 v[98:101], v[176:179], v[210:213], v[98:101]
	v_mfma_f32_16x16x32_bf16 v[86:89], v[168:171], v[218:221], v[86:89]
	v_mfma_f32_16x16x32_bf16 v[82:85], v[176:179], v[218:221], v[82:85]
	v_mfma_f32_16x16x32_bf16 v[70:73], v[168:171], v[226:229], v[70:73]
	v_mfma_f32_16x16x32_bf16 v[66:69], v[176:179], v[226:229], v[66:69]
	s_barrier
	s_add_i32 s26, s28, s17
	v_lshl_add_u64 v[144:145], s[30:31], 0, v[0:1]
	s_mov_b32 m0, s26
	ds_read_b128 v[184:187], v150 offset:16384
	ds_read_b128 v[188:191], v150 offset:17408
	ds_read_b128 v[196:199], v150 offset:18432
	ds_read_b128 v[210:213], v150 offset:19456
	ds_read_b128 v[214:217], v150 offset:20480
	ds_read_b128 v[218:221], v150 offset:21504
	ds_read_b128 v[222:225], v150 offset:22528
	ds_read_b128 v[226:229], v150 offset:23552
	global_load_lds_dwordx4 v[144:145], off
	s_add_i32 m0, s26, 0x2000
	s_add_u32 s60, s30, 0x40000
	v_lshl_add_u64 v[180:181], s[30:31], 0, v[130:131]
	s_addc_u32 s61, s31, 0
	s_add_i32 s25, s25, s17
	global_load_lds_dwordx4 v[180:181], off
	v_lshl_add_u64 v[192:193], s[60:61], 0, v[0:1]
	s_mov_b32 m0, s25
	v_lshl_add_u64 v[202:203], s[36:37], 0, v[132:133]
	global_load_lds_dwordx4 v[192:193], off
	v_lshl_add_u64 v[192:193], s[60:61], 0, v[130:131]
	s_add_i32 m0, s25, 0x2000
	s_nop 0
	global_load_lds_dwordx4 v[192:193], off
	v_lshl_add_u64 v[192:193], s[36:37], 0, v[134:135]
	s_mov_b32 m0, s47
	s_nop 0
	global_load_lds_dwordx4 v[192:193], off
	s_mov_b32 m0, s48
	s_nop 0
	global_load_lds_dwordx4 v[202:203], off
	s_waitcnt vmcnt(8)
	s_waitcnt lgkmcnt(0)
	s_barrier
	s_waitcnt lgkmcnt(0)
	v_mfma_f32_16x16x32_bf16 v[62:65], v[140:143], v[184:187], v[62:65]
	v_mfma_f32_16x16x32_bf16 v[58:61], v[156:159], v[184:187], v[58:61]
	v_mfma_f32_16x16x32_bf16 v[46:49], v[140:143], v[196:199], v[46:49]
	v_mfma_f32_16x16x32_bf16 v[42:45], v[156:159], v[196:199], v[42:45]
	v_mfma_f32_16x16x32_bf16 v[30:33], v[140:143], v[214:217], v[30:33]
	v_mfma_f32_16x16x32_bf16 v[26:29], v[156:159], v[214:217], v[26:29]
	v_mfma_f32_16x16x32_bf16 v[14:17], v[140:143], v[222:225], v[14:17]
	v_mfma_f32_16x16x32_bf16 v[10:13], v[156:159], v[222:225], v[10:13]
	v_mfma_f32_16x16x32_bf16 v[62:65], v[152:155], v[188:191], v[62:65]
	v_mfma_f32_16x16x32_bf16 v[58:61], v[160:163], v[188:191], v[58:61]
	v_mfma_f32_16x16x32_bf16 v[46:49], v[152:155], v[210:213], v[46:49]
	v_mfma_f32_16x16x32_bf16 v[42:45], v[160:163], v[210:213], v[42:45]
	v_mfma_f32_16x16x32_bf16 v[30:33], v[152:155], v[218:221], v[30:33]
	v_mfma_f32_16x16x32_bf16 v[26:29], v[160:163], v[218:221], v[26:29]
	v_mfma_f32_16x16x32_bf16 v[14:17], v[152:155], v[226:229], v[14:17]
	v_mfma_f32_16x16x32_bf16 v[10:13], v[160:163], v[226:229], v[10:13]
	v_mfma_f32_16x16x32_bf16 v[54:57], v[164:167], v[184:187], v[54:57]
	v_mfma_f32_16x16x32_bf16 v[50:53], v[172:175], v[184:187], v[50:53]
	v_mfma_f32_16x16x32_bf16 v[38:41], v[164:167], v[196:199], v[38:41]
	v_mfma_f32_16x16x32_bf16 v[34:37], v[172:175], v[196:199], v[34:37]
	v_mfma_f32_16x16x32_bf16 v[22:25], v[164:167], v[214:217], v[22:25]
	v_mfma_f32_16x16x32_bf16 v[18:21], v[172:175], v[214:217], v[18:21]
	v_mfma_f32_16x16x32_bf16 v[6:9], v[164:167], v[222:225], v[6:9]
	v_mfma_f32_16x16x32_bf16 v[2:5], v[172:175], v[222:225], v[2:5]
	v_mfma_f32_16x16x32_bf16 v[54:57], v[168:171], v[188:191], v[54:57]
	v_mfma_f32_16x16x32_bf16 v[50:53], v[176:179], v[188:191], v[50:53]
	v_mfma_f32_16x16x32_bf16 v[38:41], v[168:171], v[210:213], v[38:41]
	v_mfma_f32_16x16x32_bf16 v[34:37], v[176:179], v[210:213], v[34:37]
	v_mfma_f32_16x16x32_bf16 v[22:25], v[168:171], v[218:221], v[22:25]
	v_mfma_f32_16x16x32_bf16 v[18:21], v[176:179], v[218:221], v[18:21]
	v_mfma_f32_16x16x32_bf16 v[6:9], v[168:171], v[226:229], v[6:9]
	v_mfma_f32_16x16x32_bf16 v[2:5], v[176:179], v[226:229], v[2:5]
	s_barrier
	s_add_i32 s25, 0, 0x18000
	v_add_u32_e32 v151, s25, v147
	s_add_i32 s26, 0, 0x1c000
	ds_read_b128 v[140:143], v151
	ds_read_b128 v[152:155], v151 offset:1024
	ds_read_b128 v[156:159], v151 offset:2048
	ds_read_b128 v[160:163], v151 offset:3072
	v_add_u32_e32 v151, s26, v147
	ds_read_b128 v[164:167], v151
	ds_read_b128 v[168:171], v151 offset:1024
	ds_read_b128 v[172:175], v151 offset:2048
	ds_read_b128 v[176:179], v151 offset:3072
	s_add_u32 s36, s36, 0x40000
	s_addc_u32 s37, s37, 0
	s_mov_b32 m0, s49
	v_lshl_add_u64 v[230:231], s[36:37], 0, v[134:135]
	ds_read_b128 v[184:187], v150 offset:32768
	ds_read_b128 v[188:191], v150 offset:33792
	ds_read_b128 v[196:199], v150 offset:34816
	ds_read_b128 v[210:213], v150 offset:35840
	ds_read_b128 v[214:217], v150 offset:36864
	ds_read_b128 v[218:221], v150 offset:37888
	ds_read_b128 v[222:225], v150 offset:38912
	ds_read_b128 v[226:229], v150 offset:39936
	global_load_lds_dwordx4 v[230:231], off
	v_lshl_add_u64 v[230:231], s[36:37], 0, v[132:133]
	s_mov_b32 m0, s50
	s_nop 0
	global_load_lds_dwordx4 v[230:231], off
	s_waitcnt vmcnt(8)
	s_waitcnt lgkmcnt(0)
	s_barrier
	s_waitcnt lgkmcnt(0)
	v_mfma_f32_16x16x32_bf16 v[126:129], v[140:143], v[184:187], v[126:129]
	v_mfma_f32_16x16x32_bf16 v[122:125], v[156:159], v[184:187], v[122:125]
	v_mfma_f32_16x16x32_bf16 v[110:113], v[140:143], v[196:199], v[110:113]
	v_mfma_f32_16x16x32_bf16 v[106:109], v[156:159], v[196:199], v[106:109]
	v_mfma_f32_16x16x32_bf16 v[94:97], v[140:143], v[214:217], v[94:97]
	v_mfma_f32_16x16x32_bf16 v[90:93], v[156:159], v[214:217], v[90:93]
	v_mfma_f32_16x16x32_bf16 v[78:81], v[140:143], v[222:225], v[78:81]
	v_mfma_f32_16x16x32_bf16 v[74:77], v[156:159], v[222:225], v[74:77]
	v_mfma_f32_16x16x32_bf16 v[126:129], v[152:155], v[188:191], v[126:129]
	v_mfma_f32_16x16x32_bf16 v[122:125], v[160:163], v[188:191], v[122:125]
	v_mfma_f32_16x16x32_bf16 v[110:113], v[152:155], v[210:213], v[110:113]
	v_mfma_f32_16x16x32_bf16 v[106:109], v[160:163], v[210:213], v[106:109]
	v_mfma_f32_16x16x32_bf16 v[94:97], v[152:155], v[218:221], v[94:97]
	v_mfma_f32_16x16x32_bf16 v[90:93], v[160:163], v[218:221], v[90:93]
	v_mfma_f32_16x16x32_bf16 v[78:81], v[152:155], v[226:229], v[78:81]
	v_mfma_f32_16x16x32_bf16 v[74:77], v[160:163], v[226:229], v[74:77]
	v_mfma_f32_16x16x32_bf16 v[118:121], v[164:167], v[184:187], v[118:121]
	v_mfma_f32_16x16x32_bf16 v[114:117], v[172:175], v[184:187], v[114:117]
	v_mfma_f32_16x16x32_bf16 v[102:105], v[164:167], v[196:199], v[102:105]
	v_mfma_f32_16x16x32_bf16 v[98:101], v[172:175], v[196:199], v[98:101]
	v_mfma_f32_16x16x32_bf16 v[86:89], v[164:167], v[214:217], v[86:89]
	v_mfma_f32_16x16x32_bf16 v[82:85], v[172:175], v[214:217], v[82:85]
	v_mfma_f32_16x16x32_bf16 v[70:73], v[164:167], v[222:225], v[70:73]
	v_mfma_f32_16x16x32_bf16 v[66:69], v[172:175], v[222:225], v[66:69]
	v_mfma_f32_16x16x32_bf16 v[118:121], v[168:171], v[188:191], v[118:121]
	v_mfma_f32_16x16x32_bf16 v[114:117], v[176:179], v[188:191], v[114:117]
	v_mfma_f32_16x16x32_bf16 v[102:105], v[168:171], v[210:213], v[102:105]
	v_mfma_f32_16x16x32_bf16 v[98:101], v[176:179], v[210:213], v[98:101]
	v_mfma_f32_16x16x32_bf16 v[86:89], v[168:171], v[218:221], v[86:89]
	v_mfma_f32_16x16x32_bf16 v[82:85], v[176:179], v[218:221], v[82:85]
	v_mfma_f32_16x16x32_bf16 v[70:73], v[168:171], v[226:229], v[70:73]
	v_mfma_f32_16x16x32_bf16 v[66:69], v[176:179], v[226:229], v[66:69]
	s_barrier
	s_add_i32 s25, s25, s17
	v_lshl_add_u64 v[144:145], v[144:145], 0, s[22:23]
	s_mov_b32 m0, s25
	ds_read_b128 v[184:187], v150 offset:49152
	ds_read_b128 v[188:191], v150 offset:50176
	ds_read_b128 v[196:199], v150 offset:51200
	ds_read_b128 v[210:213], v150 offset:52224
	ds_read_b128 v[214:217], v150 offset:53248
	ds_read_b128 v[218:221], v150 offset:54272
	ds_read_b128 v[222:225], v150 offset:55296
	ds_read_b128 v[226:229], v150 offset:56320
	global_load_lds_dwordx4 v[144:145], off
	s_add_i32 m0, s25, 0x2000
	s_add_u32 s30, s30, 0x40080
	v_lshl_add_u64 v[144:145], v[180:181], 0, s[22:23]
	s_addc_u32 s31, s31, 0
	s_add_i32 s25, s26, s17
	global_load_lds_dwordx4 v[144:145], off
	v_lshl_add_u64 v[144:145], s[30:31], 0, v[0:1]
	s_mov_b32 m0, s25
	s_nop 0
	global_load_lds_dwordx4 v[144:145], off
	v_lshl_add_u64 v[144:145], s[30:31], 0, v[130:131]
	s_add_i32 m0, s25, 0x2000
	s_nop 0
	global_load_lds_dwordx4 v[144:145], off
	v_lshl_add_u64 v[144:145], v[192:193], 0, s[22:23]
	s_mov_b32 m0, s54
	s_nop 0
	global_load_lds_dwordx4 v[144:145], off
	v_lshl_add_u64 v[144:145], v[202:203], 0, s[22:23]
	s_mov_b32 m0, s55
	s_nop 0
	global_load_lds_dwordx4 v[144:145], off
	s_waitcnt vmcnt(8)
	s_waitcnt lgkmcnt(0)
	s_barrier
	s_waitcnt lgkmcnt(0)
	v_mfma_f32_16x16x32_bf16 v[62:65], v[140:143], v[184:187], v[62:65]
	v_mfma_f32_16x16x32_bf16 v[58:61], v[156:159], v[184:187], v[58:61]
	v_mfma_f32_16x16x32_bf16 v[46:49], v[140:143], v[196:199], v[46:49]
	v_mfma_f32_16x16x32_bf16 v[42:45], v[156:159], v[196:199], v[42:45]
	v_mfma_f32_16x16x32_bf16 v[30:33], v[140:143], v[214:217], v[30:33]
	v_mfma_f32_16x16x32_bf16 v[26:29], v[156:159], v[214:217], v[26:29]
	v_mfma_f32_16x16x32_bf16 v[14:17], v[140:143], v[222:225], v[14:17]
	v_mfma_f32_16x16x32_bf16 v[10:13], v[156:159], v[222:225], v[10:13]
	v_mfma_f32_16x16x32_bf16 v[62:65], v[152:155], v[188:191], v[62:65]
	v_mfma_f32_16x16x32_bf16 v[58:61], v[160:163], v[188:191], v[58:61]
	v_mfma_f32_16x16x32_bf16 v[46:49], v[152:155], v[210:213], v[46:49]
	v_mfma_f32_16x16x32_bf16 v[42:45], v[160:163], v[210:213], v[42:45]
	v_mfma_f32_16x16x32_bf16 v[30:33], v[152:155], v[218:221], v[30:33]
	v_mfma_f32_16x16x32_bf16 v[26:29], v[160:163], v[218:221], v[26:29]
	v_mfma_f32_16x16x32_bf16 v[14:17], v[152:155], v[226:229], v[14:17]
	v_mfma_f32_16x16x32_bf16 v[10:13], v[160:163], v[226:229], v[10:13]
	v_mfma_f32_16x16x32_bf16 v[54:57], v[164:167], v[184:187], v[54:57]
	v_mfma_f32_16x16x32_bf16 v[50:53], v[172:175], v[184:187], v[50:53]
	v_mfma_f32_16x16x32_bf16 v[38:41], v[164:167], v[196:199], v[38:41]
	v_mfma_f32_16x16x32_bf16 v[34:37], v[172:175], v[196:199], v[34:37]
	v_mfma_f32_16x16x32_bf16 v[22:25], v[164:167], v[214:217], v[22:25]
	v_mfma_f32_16x16x32_bf16 v[18:21], v[172:175], v[214:217], v[18:21]
	v_mfma_f32_16x16x32_bf16 v[6:9], v[164:167], v[222:225], v[6:9]
	v_mfma_f32_16x16x32_bf16 v[2:5], v[172:175], v[222:225], v[2:5]
	v_mfma_f32_16x16x32_bf16 v[54:57], v[168:171], v[188:191], v[54:57]
	v_mfma_f32_16x16x32_bf16 v[50:53], v[176:179], v[188:191], v[50:53]
	v_mfma_f32_16x16x32_bf16 v[38:41], v[168:171], v[210:213], v[38:41]
	v_mfma_f32_16x16x32_bf16 v[34:37], v[176:179], v[210:213], v[34:37]
	v_mfma_f32_16x16x32_bf16 v[22:25], v[168:171], v[218:221], v[22:25]
	v_mfma_f32_16x16x32_bf16 v[18:21], v[176:179], v[218:221], v[18:21]
	v_mfma_f32_16x16x32_bf16 v[6:9], v[168:171], v[226:229], v[6:9]
	v_mfma_f32_16x16x32_bf16 v[2:5], v[176:179], v[226:229], v[2:5]
	s_barrier
	s_add_i32 s24, s24, 2
	s_add_u32 s12, s12, 0x100
	s_addc_u32 s13, s13, 0
	s_add_u32 s19, s19, 0x100
	s_addc_u32 s21, s21, 0
	s_cmp_gt_u32 s24, 13
	s_cbranch_scc0 .LBB0_986
	s_and_b64 vcc, exec, s[10:11]
	s_cbranch_vccz .LBB0_989
	s_barrier
